# software-pipelined ple K-loops, hoisted attention epilogue loads (attn_c finalize, attn_d), batched sgu epilogue
# speedup vs baseline: 1.0715x; 1.0022x over previous
; DI float bflo(unsigned v) { return __uint_as_float(v << 16); }
; DI float bfhi(unsigned v) { return __uint_as_float(v & 0xffff0000u); }
;     ...
;     u16* dp = actD + (size_t)(b * SEQ + t0 + fr) * 512 + h * 128 + fq * 4;
; #pragma unroll
;     for (int dvs = 0; dvs < 8; ++dvs) {
;       u32x2 gz = *(const u32x2*)(dp + dvs * 16);
;       u32x2 ov = {pack2(o[dvs][0] * bflo(gz[0]), o[dvs][1] * bfhi(gz[0])),
;                   pack2(o[dvs][2] * bflo(gz[1]), o[dvs][3] * bfhi(gz[1]))};
;       if (!dry) *(u32x2*)(dp + dvs * 16) = ov;
;     }
;     __syncthreads();
.LBB0_367:
	s_or_b64 exec, exec, s[66:67]
	v_lshlrev_b64 v[28:29], 10, v[72:73]
	v_lshl_add_u64 v[28:29], s[4:5], 0, v[28:29]
	s_lshl_b32 s74, s58, 1
	v_lshl_add_u64 v[28:29], v[28:29], 0, s[74:75]
	v_mov_b32_e32 v71, v133
	v_lshl_add_u64 v[28:29], v[28:29], 0, v[70:71]
	global_load_dwordx2 v[86:87], v[28:29], off
	global_load_dwordx2 v[88:89], v[28:29], off offset:32
	global_load_dwordx2 v[90:91], v[28:29], off offset:64
	global_load_dwordx2 v[92:93], v[28:29], off offset:96
	global_load_dwordx2 v[94:95], v[28:29], off offset:128
	global_load_dwordx2 v[96:97], v[28:29], off offset:160
	global_load_dwordx2 v[98:99], v[28:29], off offset:192
	global_load_dwordx2 v[100:101], v[28:29], off offset:224
	s_add_i32 s57, s57, s72
	s_cmpk_lt_i32 s57, 0x400
	s_waitcnt vmcnt(7) lgkmcnt(0)
	v_lshlrev_b32_e32 v32, 16, v86
	v_and_b32_e32 v33, 0xffff0000, v86
	v_pk_mul_f32 v[32:33], v[44:45], v[32:33]
	s_nop 0
	v_cvt_pk_bf16_f32 v30, v32, v33
	v_lshlrev_b32_e32 v32, 16, v87
	v_and_b32_e32 v33, 0xffff0000, v87
	v_pk_mul_f32 v[32:33], v[46:47], v[32:33]
	s_nop 0
	v_cvt_pk_bf16_f32 v31, v32, v33
	global_store_dwordx2 v[28:29], v[30:31], off
	s_waitcnt vmcnt(7) lgkmcnt(0)
	v_lshlrev_b32_e32 v32, 16, v88
	v_and_b32_e32 v33, 0xffff0000, v88
	v_lshlrev_b32_e32 v30, 16, v89
	v_and_b32_e32 v31, 0xffff0000, v89
	v_pk_mul_f32 v[24:25], v[24:25], v[32:33]
	v_pk_mul_f32 v[26:27], v[26:27], v[30:31]
	v_cvt_pk_bf16_f32 v24, v24, v25
	v_cvt_pk_bf16_f32 v25, v26, v27
	global_store_dwordx2 v[28:29], v[24:25], off offset:32
	s_waitcnt vmcnt(7) lgkmcnt(0)
	v_lshlrev_b32_e32 v26, 16, v90
	v_and_b32_e32 v27, 0xffff0000, v90
	v_lshlrev_b32_e32 v24, 16, v91
	v_and_b32_e32 v25, 0xffff0000, v91
	v_pk_mul_f32 v[20:21], v[20:21], v[26:27]
	v_pk_mul_f32 v[22:23], v[22:23], v[24:25]
	v_cvt_pk_bf16_f32 v20, v20, v21
	v_cvt_pk_bf16_f32 v21, v22, v23
	global_store_dwordx2 v[28:29], v[20:21], off offset:64
	s_waitcnt vmcnt(7) lgkmcnt(0)
	v_lshlrev_b32_e32 v22, 16, v92
	v_and_b32_e32 v23, 0xffff0000, v92
	v_lshlrev_b32_e32 v20, 16, v93
	v_and_b32_e32 v21, 0xffff0000, v93
	v_pk_mul_f32 v[16:17], v[16:17], v[22:23]
	v_pk_mul_f32 v[18:19], v[18:19], v[20:21]
	v_cvt_pk_bf16_f32 v16, v16, v17
	v_cvt_pk_bf16_f32 v17, v18, v19
	global_store_dwordx2 v[28:29], v[16:17], off offset:96
	s_waitcnt vmcnt(7) lgkmcnt(0)
	v_lshlrev_b32_e32 v18, 16, v94
	v_and_b32_e32 v19, 0xffff0000, v94
	v_lshlrev_b32_e32 v16, 16, v95
	v_and_b32_e32 v17, 0xffff0000, v95
	v_pk_mul_f32 v[12:13], v[12:13], v[18:19]
	v_pk_mul_f32 v[14:15], v[14:15], v[16:17]
	v_cvt_pk_bf16_f32 v12, v12, v13
	v_cvt_pk_bf16_f32 v13, v14, v15
	global_store_dwordx2 v[28:29], v[12:13], off offset:128
	s_waitcnt vmcnt(7) lgkmcnt(0)
	v_lshlrev_b32_e32 v14, 16, v96
	v_and_b32_e32 v15, 0xffff0000, v96
	v_lshlrev_b32_e32 v12, 16, v97
	v_and_b32_e32 v13, 0xffff0000, v97
	v_pk_mul_f32 v[8:9], v[8:9], v[14:15]
	v_pk_mul_f32 v[10:11], v[10:11], v[12:13]
	v_cvt_pk_bf16_f32 v8, v8, v9
	v_cvt_pk_bf16_f32 v9, v10, v11
	global_store_dwordx2 v[28:29], v[8:9], off offset:160
	s_waitcnt vmcnt(7) lgkmcnt(0)
	v_lshlrev_b32_e32 v10, 16, v98
	v_and_b32_e32 v11, 0xffff0000, v98
	v_lshlrev_b32_e32 v8, 16, v99
	v_and_b32_e32 v9, 0xffff0000, v99
	v_pk_mul_f32 v[4:5], v[4:5], v[10:11]
	v_pk_mul_f32 v[6:7], v[6:7], v[8:9]
	v_cvt_pk_bf16_f32 v4, v4, v5
	v_cvt_pk_bf16_f32 v5, v6, v7
	global_store_dwordx2 v[28:29], v[4:5], off offset:192
	s_waitcnt vmcnt(7) lgkmcnt(0)
	v_lshlrev_b32_e32 v6, 16, v100
	v_and_b32_e32 v7, 0xffff0000, v100
	v_lshlrev_b32_e32 v4, 16, v101
	v_and_b32_e32 v5, 0xffff0000, v101
	v_pk_mul_f32 v[0:1], v[0:1], v[6:7]
	v_pk_mul_f32 v[2:3], v[2:3], v[4:5]
	v_cvt_pk_bf16_f32 v0, v0, v1
	v_cvt_pk_bf16_f32 v1, v2, v3
	global_store_dwordx2 v[28:29], v[0:1], off offset:224
	s_waitcnt lgkmcnt(0)
	s_barrier
	s_cbranch_scc0 .LBB0_403

; DI float bflo(unsigned v) { return __uint_as_float(v << 16); }
; DI float bfhi(unsigned v) { return __uint_as_float(v & 0xffff0000u); }
; DI void attn_c_item(const Params& P, int l, int b, int h, int qb, char* shm, float B2, int dry) {
;     ...
;     asm volatile("s_waitcnt vmcnt(0)" ::: "memory");
;     __syncthreads();
;   }
;     ...
;   u16* actC = (u16*)(P.ws + OFF_ACTC);
; #pragma unroll
;   for (int qs = 0; qs < 2; ++qs) {
;     float lt = lsum[qs];
;     lt += __shfl_xor(lt, 16);
;     lt += __shfl_xor(lt, 32);
;     const float inv = 1.f / lt;
;     u16* dp = actC + (size_t)(b * SEQ + q0 + qs * 16 + fr) * 512 + h * 128 + fq * 4;
; #pragma unroll
;     for (int dvs = 0; dvs < 8; ++dvs) {
;       u32x2 gz = *(const u32x2*)(dp + dvs * 16);
;       u32x2 ov = {pack2(o[dvs][qs][0] * inv * bflo(gz[0]), o[dvs][qs][1] * inv * bfhi(gz[0])),
;                   pack2(o[dvs][qs][2] * inv * bflo(gz[1]), o[dvs][qs][3] * inv * bfhi(gz[1]))};
;       if (!dry) *(u32x2*)(dp + dvs * 16) = ov;
.LBB0_580:
	s_waitcnt vmcnt(0)
	v_add_u32_e32 v122, 0x3000, v122
	v_add_u32_e32 v123, 0x3000, v123
	v_add_u32_e32 v124, 0x3000, v124
	v_add_u32_e32 v125, 64, v125
	s_cmp_lg_u32 s0, s35
	v_add_u32_e32 v126, 64, v126
	s_waitcnt vmcnt(0) lgkmcnt(0)
	s_barrier
	s_cbranch_scc1 .LBB0_576
	ds_bpermute_b32 v32, v212, v119
	v_lshlrev_b32_e32 v132, 1, v116
	v_lshl_add_u64 v[34:35], s[18:19], 0, v[132:133]
	s_waitcnt lgkmcnt(0)
	v_add_f32_e32 v32, v119, v32
	ds_bpermute_b32 v33, v211, v32
	s_waitcnt lgkmcnt(0)
	v_add_f32_e32 v32, v32, v33
	v_div_scale_f32 v33, s[0:1], v32, v32, 1.0
	v_rcp_f32_e32 v36, v33
	s_nop 0
	v_fma_f32 v37, -v33, v36, 1.0
	v_fmac_f32_e32 v36, v37, v36
	v_div_scale_f32 v37, vcc, 1.0, v32, 1.0
	v_mul_f32_e32 v38, v37, v36
	v_fma_f32 v39, -v33, v38, v37
	v_fmac_f32_e32 v38, v39, v36
	v_fma_f32 v33, -v33, v38, v37
	v_div_fmas_f32 v33, v33, v36, v38
	v_lshlrev_b64 v[36:37], 10, v[114:115]
	v_lshl_add_u64 v[36:37], v[34:35], 0, v[36:37]
	global_load_dwordx2 v[230:231], v[36:37], off
	global_load_dwordx2 v[232:233], v[36:37], off offset:32
	global_load_dwordx2 v[234:235], v[36:37], off offset:64
	global_load_dwordx2 v[236:237], v[36:37], off offset:96
	global_load_dwordx2 v[238:239], v[36:37], off offset:128
	global_load_dwordx2 v[240:241], v[36:37], off offset:160
	global_load_dwordx2 v[242:243], v[36:37], off offset:192
	global_load_dwordx2 v[244:245], v[36:37], off offset:224
	v_div_fixup_f32 v32, v33, v32, 1.0
	v_pk_mul_f32 v[44:45], v[104:105], v[32:33] op_sel_hi:[1,0]
	v_pk_mul_f32 v[40:41], v[40:41], v[32:33] op_sel_hi:[1,0]
	s_waitcnt vmcnt(7) lgkmcnt(0)
	v_lshlrev_b32_e32 v46, 16, v230
	v_and_b32_e32 v47, 0xffff0000, v230
	v_pk_mul_f32 v[44:45], v[44:45], v[46:47]
	v_lshlrev_b32_e32 v46, 16, v231
	v_cvt_pk_bf16_f32 v38, v44, v45
	v_pk_mul_f32 v[44:45], v[106:107], v[32:33] op_sel_hi:[1,0]
	v_and_b32_e32 v47, 0xffff0000, v231
	v_pk_mul_f32 v[44:45], v[44:45], v[46:47]
	s_nop 0
	v_cvt_pk_bf16_f32 v39, v44, v45
	global_store_dwordx2 v[36:37], v[38:39], off
	v_pk_mul_f32 v[44:45], v[96:97], v[32:33] op_sel_hi:[1,0]
	s_waitcnt vmcnt(7) lgkmcnt(0)
	v_lshlrev_b32_e32 v46, 16, v232
	v_and_b32_e32 v47, 0xffff0000, v232
	v_pk_mul_f32 v[44:45], v[44:45], v[46:47]
	v_lshlrev_b32_e32 v46, 16, v233
	v_cvt_pk_bf16_f32 v38, v44, v45
	v_pk_mul_f32 v[44:45], v[98:99], v[32:33] op_sel_hi:[1,0]
	v_and_b32_e32 v47, 0xffff0000, v233
	v_pk_mul_f32 v[44:45], v[44:45], v[46:47]
	s_nop 0
	v_cvt_pk_bf16_f32 v39, v44, v45
	global_store_dwordx2 v[36:37], v[38:39], off offset:32
	v_pk_mul_f32 v[44:45], v[92:93], v[32:33] op_sel_hi:[1,0]
	s_waitcnt vmcnt(7) lgkmcnt(0)
	v_lshlrev_b32_e32 v46, 16, v234
	v_and_b32_e32 v47, 0xffff0000, v234
	v_pk_mul_f32 v[44:45], v[44:45], v[46:47]
	v_lshlrev_b32_e32 v46, 16, v235
	v_cvt_pk_bf16_f32 v38, v44, v45
	v_pk_mul_f32 v[44:45], v[94:95], v[32:33] op_sel_hi:[1,0]
	v_and_b32_e32 v47, 0xffff0000, v235
	v_pk_mul_f32 v[44:45], v[44:45], v[46:47]
	s_nop 0
	v_cvt_pk_bf16_f32 v39, v44, v45
	global_store_dwordx2 v[36:37], v[38:39], off offset:64
	v_pk_mul_f32 v[44:45], v[72:73], v[32:33] op_sel_hi:[1,0]
	s_waitcnt vmcnt(7) lgkmcnt(0)
	v_lshlrev_b32_e32 v46, 16, v236
	v_and_b32_e32 v47, 0xffff0000, v236
	v_pk_mul_f32 v[44:45], v[44:45], v[46:47]
	v_lshlrev_b32_e32 v46, 16, v237
	v_cvt_pk_bf16_f32 v38, v44, v45
	v_pk_mul_f32 v[44:45], v[74:75], v[32:33] op_sel_hi:[1,0]
	v_and_b32_e32 v47, 0xffff0000, v237
	v_pk_mul_f32 v[44:45], v[44:45], v[46:47]
	s_nop 0
	v_cvt_pk_bf16_f32 v39, v44, v45
	global_store_dwordx2 v[36:37], v[38:39], off offset:96
	v_pk_mul_f32 v[44:45], v[64:65], v[32:33] op_sel_hi:[1,0]
	s_waitcnt vmcnt(7) lgkmcnt(0)
	v_lshlrev_b32_e32 v46, 16, v238
	v_and_b32_e32 v47, 0xffff0000, v238
	v_pk_mul_f32 v[44:45], v[44:45], v[46:47]
	v_lshlrev_b32_e32 v46, 16, v239
	v_cvt_pk_bf16_f32 v38, v44, v45
	v_pk_mul_f32 v[44:45], v[66:67], v[32:33] op_sel_hi:[1,0]
	v_and_b32_e32 v47, 0xffff0000, v239
	v_pk_mul_f32 v[44:45], v[44:45], v[46:47]
	s_nop 0
	v_cvt_pk_bf16_f32 v39, v44, v45
	global_store_dwordx2 v[36:37], v[38:39], off offset:128
	v_pk_mul_f32 v[44:45], v[52:53], v[32:33] op_sel_hi:[1,0]
	s_waitcnt vmcnt(7) lgkmcnt(0)
	v_lshlrev_b32_e32 v46, 16, v240
	v_and_b32_e32 v47, 0xffff0000, v240
	v_pk_mul_f32 v[44:45], v[44:45], v[46:47]
	v_lshlrev_b32_e32 v46, 16, v241
	v_cvt_pk_bf16_f32 v38, v44, v45
	v_pk_mul_f32 v[44:45], v[54:55], v[32:33] op_sel_hi:[1,0]
	v_and_b32_e32 v47, 0xffff0000, v241
	v_pk_mul_f32 v[44:45], v[44:45], v[46:47]
	s_nop 0
	v_cvt_pk_bf16_f32 v39, v44, v45
	global_store_dwordx2 v[36:37], v[38:39], off offset:160
	v_pk_mul_f32 v[44:45], v[48:49], v[32:33] op_sel_hi:[1,0]
	s_waitcnt vmcnt(7) lgkmcnt(0)
	v_lshlrev_b32_e32 v46, 16, v242
	v_and_b32_e32 v47, 0xffff0000, v242
	v_pk_mul_f32 v[44:45], v[44:45], v[46:47]
	v_lshlrev_b32_e32 v46, 16, v243
	v_cvt_pk_bf16_f32 v38, v44, v45
	v_pk_mul_f32 v[44:45], v[50:51], v[32:33] op_sel_hi:[1,0]
	v_and_b32_e32 v47, 0xffff0000, v243
	v_pk_mul_f32 v[44:45], v[44:45], v[46:47]
	v_pk_mul_f32 v[32:33], v[42:43], v[32:33] op_sel_hi:[1,0]
	v_cvt_pk_bf16_f32 v39, v44, v45
	global_store_dwordx2 v[36:37], v[38:39], off offset:192
	s_waitcnt vmcnt(7) lgkmcnt(0)
	v_lshlrev_b32_e32 v44, 16, v244
	v_and_b32_e32 v45, 0xffff0000, v244
	v_pk_mul_f32 v[40:41], v[40:41], v[44:45]
	s_nop 0
	v_cvt_pk_bf16_f32 v38, v40, v41
	v_lshlrev_b32_e32 v40, 16, v245
	v_and_b32_e32 v41, 0xffff0000, v245
	v_pk_mul_f32 v[32:33], v[32:33], v[40:41]
	s_nop 0
	v_cvt_pk_bf16_f32 v39, v32, v33
	ds_bpermute_b32 v32, v212, v118
	global_store_dwordx2 v[36:37], v[38:39], off offset:224
	s_waitcnt lgkmcnt(0)
; DI float bflo(unsigned v) { return __uint_as_float(v << 16); }
; DI float bfhi(unsigned v) { return __uint_as_float(v & 0xffff0000u); }
; DI void attn_c_item(const Params& P, int l, int b, int h, int qb, char* shm, float B2, int dry) {
;     ...
;   for (int qs = 0; qs < 2; ++qs) {
;     float lt = lsum[qs];
;     lt += __shfl_xor(lt, 16);
;     lt += __shfl_xor(lt, 32);
;     const float inv = 1.f / lt;
;     u16* dp = actC + (size_t)(b * SEQ + q0 + qs * 16 + fr) * 512 + h * 128 + fq * 4;
; #pragma unroll
;     for (int dvs = 0; dvs < 8; ++dvs) {
;       u32x2 gz = *(const u32x2*)(dp + dvs * 16);
;       u32x2 ov = {pack2(o[dvs][qs][0] * inv * bflo(gz[0]), o[dvs][qs][1] * inv * bfhi(gz[0])),
;                   pack2(o[dvs][qs][2] * inv * bflo(gz[1]), o[dvs][qs][3] * inv * bfhi(gz[1]))};
;       if (!dry) *(u32x2*)(dp + dvs * 16) = ov;
;     }
;   }
; DI void phase_attn_c(const Params& P, int l, char* shm, int dry) {
;     ...
;   for (int it = blockIdx.x; it < 256; it += gridDim.x) {
;     const int bh = it >> 4, pr = it & 15, b = bh >> 2, h = bh & 3;
; #pragma clang loop unroll(disable)
;     for (int hf = 0; hf < 2; ++hf) attn_c_item(P, l, b, h, hf ? pr : 31 - pr, shm, B2, dry);
	v_add_f32_e32 v32, v118, v32
	ds_bpermute_b32 v33, v211, v32
	s_waitcnt lgkmcnt(0)
	v_add_f32_e32 v32, v32, v33
	v_div_scale_f32 v33, s[0:1], v32, v32, 1.0
	v_rcp_f32_e32 v36, v33
	s_mov_b64 s[0:1], 0
	v_fma_f32 v37, -v33, v36, 1.0
	v_fmac_f32_e32 v36, v37, v36
	v_div_scale_f32 v37, vcc, 1.0, v32, 1.0
	v_mul_f32_e32 v38, v37, v36
	v_fma_f32 v39, -v33, v38, v37
	v_fmac_f32_e32 v38, v39, v36
	v_fma_f32 v33, -v33, v38, v37
	v_div_fmas_f32 v33, v33, v36, v38
	v_lshlrev_b64 v[36:37], 10, v[112:113]
	v_lshl_add_u64 v[34:35], v[34:35], 0, v[36:37]
	global_load_dwordx2 v[230:231], v[34:35], off
	global_load_dwordx2 v[232:233], v[34:35], off offset:32
	global_load_dwordx2 v[234:235], v[34:35], off offset:64
	global_load_dwordx2 v[236:237], v[34:35], off offset:96
	global_load_dwordx2 v[238:239], v[34:35], off offset:128
	global_load_dwordx2 v[240:241], v[34:35], off offset:160
	global_load_dwordx2 v[242:243], v[34:35], off offset:192
	global_load_dwordx2 v[244:245], v[34:35], off offset:224
	v_div_fixup_f32 v32, v33, v32, 1.0
	v_pk_mul_f32 v[28:29], v[28:29], v[32:33] op_sel_hi:[1,0]
	v_pk_mul_f32 v[30:31], v[30:31], v[32:33] op_sel_hi:[1,0]
	v_pk_mul_f32 v[24:25], v[24:25], v[32:33] op_sel_hi:[1,0]
	v_pk_mul_f32 v[26:27], v[26:27], v[32:33] op_sel_hi:[1,0]
	v_pk_mul_f32 v[20:21], v[20:21], v[32:33] op_sel_hi:[1,0]
	v_pk_mul_f32 v[22:23], v[22:23], v[32:33] op_sel_hi:[1,0]
	v_pk_mul_f32 v[16:17], v[16:17], v[32:33] op_sel_hi:[1,0]
	v_pk_mul_f32 v[18:19], v[18:19], v[32:33] op_sel_hi:[1,0]
	v_pk_mul_f32 v[12:13], v[12:13], v[32:33] op_sel_hi:[1,0]
	v_pk_mul_f32 v[14:15], v[14:15], v[32:33] op_sel_hi:[1,0]
	v_pk_mul_f32 v[8:9], v[8:9], v[32:33] op_sel_hi:[1,0]
	v_pk_mul_f32 v[10:11], v[10:11], v[32:33] op_sel_hi:[1,0]
	v_pk_mul_f32 v[4:5], v[4:5], v[32:33] op_sel_hi:[1,0]
	v_pk_mul_f32 v[6:7], v[6:7], v[32:33] op_sel_hi:[1,0]
	v_pk_mul_f32 v[0:1], v[0:1], v[32:33] op_sel_hi:[1,0]
	v_pk_mul_f32 v[2:3], v[2:3], v[32:33] op_sel_hi:[1,0]
	s_and_b64 vcc, exec, s[20:21]
	s_waitcnt vmcnt(7) lgkmcnt(0)
	v_lshlrev_b32_e32 v38, 16, v230
	v_and_b32_e32 v39, 0xffff0000, v230
	v_lshlrev_b32_e32 v36, 16, v231
	v_and_b32_e32 v37, 0xffff0000, v231
	v_pk_mul_f32 v[28:29], v[28:29], v[38:39]
	v_pk_mul_f32 v[30:31], v[30:31], v[36:37]
	v_cvt_pk_bf16_f32 v28, v28, v29
	v_cvt_pk_bf16_f32 v29, v30, v31
	global_store_dwordx2 v[34:35], v[28:29], off
	s_waitcnt vmcnt(7) lgkmcnt(0)
	v_lshlrev_b32_e32 v30, 16, v232
	v_and_b32_e32 v31, 0xffff0000, v232
	v_lshlrev_b32_e32 v28, 16, v233
	v_and_b32_e32 v29, 0xffff0000, v233
	v_pk_mul_f32 v[24:25], v[24:25], v[30:31]
	v_pk_mul_f32 v[26:27], v[26:27], v[28:29]
	v_cvt_pk_bf16_f32 v24, v24, v25
	v_cvt_pk_bf16_f32 v25, v26, v27
	global_store_dwordx2 v[34:35], v[24:25], off offset:32
	s_waitcnt vmcnt(7) lgkmcnt(0)
	v_lshlrev_b32_e32 v26, 16, v234
	v_and_b32_e32 v27, 0xffff0000, v234
	v_lshlrev_b32_e32 v24, 16, v235
	v_and_b32_e32 v25, 0xffff0000, v235
	v_pk_mul_f32 v[20:21], v[20:21], v[26:27]
	v_pk_mul_f32 v[22:23], v[22:23], v[24:25]
	v_cvt_pk_bf16_f32 v20, v20, v21
	v_cvt_pk_bf16_f32 v21, v22, v23
	global_store_dwordx2 v[34:35], v[20:21], off offset:64
	s_waitcnt vmcnt(7) lgkmcnt(0)
	v_lshlrev_b32_e32 v22, 16, v236
	v_and_b32_e32 v23, 0xffff0000, v236
	v_lshlrev_b32_e32 v20, 16, v237
	v_and_b32_e32 v21, 0xffff0000, v237
	v_pk_mul_f32 v[16:17], v[16:17], v[22:23]
	v_pk_mul_f32 v[18:19], v[18:19], v[20:21]
	v_cvt_pk_bf16_f32 v16, v16, v17
	v_cvt_pk_bf16_f32 v17, v18, v19
	global_store_dwordx2 v[34:35], v[16:17], off offset:96
	s_waitcnt vmcnt(7) lgkmcnt(0)
	v_lshlrev_b32_e32 v18, 16, v238
	v_and_b32_e32 v19, 0xffff0000, v238
	v_lshlrev_b32_e32 v16, 16, v239
	v_and_b32_e32 v17, 0xffff0000, v239
	v_pk_mul_f32 v[12:13], v[12:13], v[18:19]
	v_pk_mul_f32 v[14:15], v[14:15], v[16:17]
	v_cvt_pk_bf16_f32 v12, v12, v13
	v_cvt_pk_bf16_f32 v13, v14, v15
	global_store_dwordx2 v[34:35], v[12:13], off offset:128
	s_waitcnt vmcnt(7) lgkmcnt(0)
	v_lshlrev_b32_e32 v14, 16, v240
	v_and_b32_e32 v15, 0xffff0000, v240
	v_lshlrev_b32_e32 v12, 16, v241
	v_and_b32_e32 v13, 0xffff0000, v241
	v_pk_mul_f32 v[8:9], v[8:9], v[14:15]
	v_pk_mul_f32 v[10:11], v[10:11], v[12:13]
	v_cvt_pk_bf16_f32 v8, v8, v9
	v_cvt_pk_bf16_f32 v9, v10, v11
	global_store_dwordx2 v[34:35], v[8:9], off offset:160
	s_waitcnt vmcnt(7) lgkmcnt(0)
	v_lshlrev_b32_e32 v10, 16, v242
	v_and_b32_e32 v11, 0xffff0000, v242
	v_lshlrev_b32_e32 v8, 16, v243
	v_and_b32_e32 v9, 0xffff0000, v243
	v_pk_mul_f32 v[4:5], v[4:5], v[10:11]
	v_pk_mul_f32 v[6:7], v[6:7], v[8:9]
	v_cvt_pk_bf16_f32 v4, v4, v5
	v_cvt_pk_bf16_f32 v5, v6, v7
	global_store_dwordx2 v[34:35], v[4:5], off offset:192
	s_waitcnt vmcnt(7) lgkmcnt(0)
	v_lshlrev_b32_e32 v6, 16, v244
	v_and_b32_e32 v7, 0xffff0000, v244
	v_lshlrev_b32_e32 v4, 16, v245
	v_and_b32_e32 v5, 0xffff0000, v245
	v_pk_mul_f32 v[0:1], v[0:1], v[6:7]
	v_pk_mul_f32 v[2:3], v[2:3], v[4:5]
	v_cvt_pk_bf16_f32 v0, v0, v1
	v_cvt_pk_bf16_f32 v1, v2, v3
	global_store_dwordx2 v[34:35], v[0:1], off offset:224
	s_cbranch_vccz .LBB0_575
	s_add_i32 s28, s28, s72
	s_cmpk_gt_i32 s28, 0xff
	s_cbranch_scc0 .LBB0_574
	v_readlane_b32 s50, v252, 18
	v_readlane_b32 s51, v252, 19
	s_movk_i32 s42, 0xfc0
	v_readlane_b32 s46, v252, 31
	s_mov_b64 s[34:35], 0x20000
	s_mov_b64 s[36:37], 0x8000
	s_mov_b64 s[38:39], 0x18000

; DI u16 f2bf(float a) { return (u16)(pack2(a, 0.f) & 0xffffu); }
; DI float bflo(unsigned v) { return __uint_as_float(v << 16); }
; DI float bfhi(unsigned v) { return __uint_as_float(v & 0xffff0000u); }
;     ...
;       {
;         const int s = tid >> 2, cq = tid & 3;
;         const float mean = st[s], rstd = st[128 + s];
;         const u16* p = projA + (size_t)(T0 + s) * 1024 + 512 + g * 128 + cq * 32;
; #pragma unroll
;         for (int i = 0; i < 4; ++i) {
;           i32x4 v = *(const i32x4*)(p + i * 8);
; #pragma unroll
;           for (int e = 0; e < 4; ++e) {
;             const int c = cq * 32 + i * 8 + 2 * e;
;             float a = (bflo((unsigned)v[e]) - mean) * rstd * lng[g * 128 + c] + lnb[g * 128 + c];
;             float d = (bfhi((unsigned)v[e]) - mean) * rstd * lng[g * 128 + c + 1] + lnb[g * 128 + c + 1];
;             vT[c * 136 + s] = f2bf(a);
;             vT[(c + 1) * 136 + s] = f2bf(d);
;           }
;         }
;       }
.LBB0_781:
	v_lshl_add_u64 v[2:3], s[18:19], 0, v[42:43]
	v_add_co_u32_e32 v10, vcc, 0x19000000, v2
	ds_read2st64_b32 v[0:1], v64 offset0:136 offset1:138
	s_nop 0
	v_addc_co_u32_e32 v11, vcc, 0, v3, vcc
	global_load_dwordx4 v[136:139], v[10:11], off offset:1024
	global_load_dwordx4 v[140:143], v[10:11], off offset:1040
	global_load_dwordx4 v[144:147], v[10:11], off offset:1056
	global_load_dwordx4 v[148:151], v[10:11], off offset:1072
	v_lshl_add_u64 v[62:63], v[24:25], 0, s[16:17]
	v_lshl_add_u64 v[124:125], v[26:27], 0, s[16:17]
	v_ashrrev_i32_e32 v53, 31, v52
	s_add_u32 s16, s16, 0x200
	s_addc_u32 s17, s17, 0
	s_waitcnt vmcnt(3) lgkmcnt(0)
	v_lshlrev_b32_e32 v6, 16, v136
	v_sub_f32_e32 v6, v6, v0
	v_mul_f32_e32 v17, v1, v6
	global_load_dwordx4 v[6:9], v[62:63], off offset:48
	global_load_dwordx4 v[54:57], v[62:63], off offset:32
	global_load_dwordx4 v[58:61], v[62:63], off offset:16
	global_load_dwordx4 v[104:107], v[62:63], off
	global_load_dwordx4 v[108:111], v[124:125], off offset:48
	global_load_dwordx4 v[112:115], v[124:125], off offset:32
	global_load_dwordx4 v[116:119], v[124:125], off offset:16
	global_load_dwordx4 v[120:123], v[124:125], off
	v_and_b32_e32 v2, 0xffff0000, v136
	v_sub_f32_e32 v2, v2, v0
	v_mul_f32_e32 v2, v1, v2
	s_waitcnt vmcnt(0)
	v_fma_f32 v17, v104, v17, v120
	v_fma_f32 v2, v105, v2, v121
	v_cvt_pk_bf16_f32 v17, v17, s0
	v_cvt_pk_bf16_f32 v2, v2, s0
	ds_write_b16 v66, v17
	ds_write_b16 v67, v2 offset:272
	v_lshlrev_b32_e32 v2, 16, v137
	v_sub_f32_e32 v2, v2, v0
	v_and_b32_e32 v3, 0xffff0000, v137
	v_mul_f32_e32 v2, v1, v2
	v_sub_f32_e32 v3, v3, v0
	v_fma_f32 v2, v2, v106, v122
	v_mul_f32_e32 v3, v1, v3
	v_fmac_f32_e32 v123, v3, v107
	v_cvt_pk_bf16_f32 v2, v2, s0
	ds_write_b16 v68, v2
	v_cvt_pk_bf16_f32 v2, v123, s0
	ds_write_b16 v69, v2 offset:272
	v_lshlrev_b32_e32 v2, 16, v138
	v_sub_f32_e32 v2, v2, v0
	v_and_b32_e32 v3, 0xffff0000, v138
	v_mul_f32_e32 v2, v1, v2
	v_sub_f32_e32 v3, v3, v0
	v_fma_f32 v2, v2, v58, v116
	v_mul_f32_e32 v3, v1, v3
	v_fma_f32 v3, v3, v59, v117
	v_cvt_pk_bf16_f32 v2, v2, s0
	ds_write_b16 v70, v2
	v_cvt_pk_bf16_f32 v2, v3, s0
	ds_write_b16 v71, v2 offset:272
	v_lshlrev_b32_e32 v2, 16, v139
	v_sub_f32_e32 v2, v2, v0
	v_and_b32_e32 v3, 0xffff0000, v139
	v_mul_f32_e32 v2, v1, v2
	v_sub_f32_e32 v3, v3, v0
	v_fma_f32 v2, v2, v60, v118
	v_mul_f32_e32 v3, v1, v3
	v_fmac_f32_e32 v119, v3, v61
	v_cvt_pk_bf16_f32 v2, v2, s0
	ds_write_b16 v72, v2
	v_cvt_pk_bf16_f32 v2, v119, s0
	ds_write_b16 v73, v2 offset:272
	s_waitcnt vmcnt(2) lgkmcnt(0)
	v_lshlrev_b32_e32 v17, 16, v140
	v_and_b32_e32 v2, 0xffff0000, v140
	v_sub_f32_e32 v17, v17, v0
	v_sub_f32_e32 v2, v2, v0
	v_mul_f32_e32 v17, v1, v17
	v_mul_f32_e32 v2, v1, v2
	v_fma_f32 v17, v54, v17, v112
	v_fma_f32 v2, v55, v2, v113
	v_cvt_pk_bf16_f32 v17, v17, s0
	v_cvt_pk_bf16_f32 v2, v2, s0
	ds_write_b16 v74, v17
	ds_write_b16 v75, v2 offset:272
	v_lshlrev_b32_e32 v2, 16, v141
	v_sub_f32_e32 v2, v2, v0
	v_and_b32_e32 v3, 0xffff0000, v141
	v_mul_f32_e32 v2, v1, v2
	v_sub_f32_e32 v3, v3, v0
	v_fma_f32 v2, v2, v56, v114
	v_mul_f32_e32 v3, v1, v3
	v_fmac_f32_e32 v115, v3, v57
	v_cvt_pk_bf16_f32 v2, v2, s0
	ds_write_b16 v76, v2
	v_cvt_pk_bf16_f32 v2, v115, s0
	ds_write_b16 v77, v2 offset:272
	v_lshlrev_b32_e32 v2, 16, v142
	v_sub_f32_e32 v2, v2, v0
	v_and_b32_e32 v3, 0xffff0000, v142
	v_mul_f32_e32 v2, v1, v2
	v_sub_f32_e32 v3, v3, v0
	v_fma_f32 v2, v2, v6, v108
	v_mul_f32_e32 v3, v1, v3
	v_fma_f32 v3, v3, v7, v109
	v_cvt_pk_bf16_f32 v2, v2, s0
	ds_write_b16 v78, v2
	v_cvt_pk_bf16_f32 v2, v3, s0
	ds_write_b16 v79, v2 offset:272
	v_lshlrev_b32_e32 v2, 16, v143
	v_sub_f32_e32 v2, v2, v0
	v_and_b32_e32 v3, 0xffff0000, v143
	v_mul_f32_e32 v2, v1, v2
	v_sub_f32_e32 v3, v3, v0
	v_fma_f32 v2, v2, v8, v110
	v_mul_f32_e32 v3, v1, v3
	v_fmac_f32_e32 v111, v3, v9
	v_cvt_pk_bf16_f32 v2, v2, s0
	ds_write_b16 v80, v2
	v_cvt_pk_bf16_f32 v2, v111, s0
	ds_write_b16 v81, v2 offset:272
	s_waitcnt vmcnt(1) lgkmcnt(0)
	v_lshlrev_b32_e32 v6, 16, v144
	v_sub_f32_e32 v6, v6, v0
	v_mul_f32_e32 v17, v1, v6
	global_load_dwordx4 v[6:9], v[62:63], off offset:112
	global_load_dwordx4 v[54:57], v[62:63], off offset:96
	global_load_dwordx4 v[58:61], v[62:63], off offset:80
	global_load_dwordx4 v[104:107], v[62:63], off offset:64
	global_load_dwordx4 v[108:111], v[124:125], off offset:112
	global_load_dwordx4 v[112:115], v[124:125], off offset:96
	global_load_dwordx4 v[116:119], v[124:125], off offset:80
	global_load_dwordx4 v[120:123], v[124:125], off offset:64
	v_and_b32_e32 v2, 0xffff0000, v144
	v_sub_f32_e32 v2, v2, v0
	v_mul_f32_e32 v2, v1, v2
	s_waitcnt vmcnt(0)
	v_fma_f32 v17, v104, v17, v120
	v_fma_f32 v2, v105, v2, v121
	v_cvt_pk_bf16_f32 v17, v17, s0
	v_cvt_pk_bf16_f32 v2, v2, s0
	ds_write_b16 v82, v17
	ds_write_b16 v83, v2 offset:272
	v_lshlrev_b32_e32 v2, 16, v145
	v_sub_f32_e32 v2, v2, v0
	v_and_b32_e32 v3, 0xffff0000, v145
	v_mul_f32_e32 v2, v1, v2
	v_sub_f32_e32 v3, v3, v0
	v_fma_f32 v2, v2, v106, v122
	v_mul_f32_e32 v3, v1, v3
	v_fmac_f32_e32 v123, v3, v107
	v_cvt_pk_bf16_f32 v2, v2, s0
	ds_write_b16 v84, v2
	v_cvt_pk_bf16_f32 v2, v123, s0
	ds_write_b16 v85, v2 offset:272
	v_lshlrev_b32_e32 v2, 16, v146
	v_sub_f32_e32 v2, v2, v0
	v_and_b32_e32 v3, 0xffff0000, v146
	v_mul_f32_e32 v2, v1, v2
	v_sub_f32_e32 v3, v3, v0
	v_fma_f32 v2, v2, v58, v116
	v_mul_f32_e32 v3, v1, v3
	v_fma_f32 v3, v3, v59, v117
	v_cvt_pk_bf16_f32 v2, v2, s0
	ds_write_b16 v86, v2
	v_cvt_pk_bf16_f32 v2, v3, s0
	ds_write_b16 v87, v2 offset:272
	v_lshlrev_b32_e32 v2, 16, v147
	v_sub_f32_e32 v2, v2, v0
	v_and_b32_e32 v3, 0xffff0000, v147
	v_mul_f32_e32 v2, v1, v2
	v_sub_f32_e32 v3, v3, v0
	v_fma_f32 v2, v2, v60, v118
	v_mul_f32_e32 v3, v1, v3
	v_fmac_f32_e32 v119, v3, v61
	v_cvt_pk_bf16_f32 v2, v2, s0
	ds_write_b16 v88, v2
	v_cvt_pk_bf16_f32 v2, v119, s0
	ds_write_b16 v89, v2 offset:272
	s_waitcnt vmcnt(0) lgkmcnt(0)
; #define MFMA16(a, b, c) __builtin_amdgcn_mfma_f32_16x16x32_bf16((a), (b), (c), 0, 0, 0)
; DI u16 f2bf(float a) { return (u16)(pack2(a, 0.f) & 0xffffu); }
; DI float bflo(unsigned v) { return __uint_as_float(v << 16); }
; DI float bfhi(unsigned v) { return __uint_as_float(v & 0xffff0000u); }
;     ...
;             float a = (bflo((unsigned)v[e]) - mean) * rstd * lng[g * 128 + c] + lnb[g * 128 + c];
;             float d = (bfhi((unsigned)v[e]) - mean) * rstd * lng[g * 128 + c + 1] + lnb[g * 128 + c + 1];
;             vT[c * 136 + s] = f2bf(a);
;             vT[(c + 1) * 136 + s] = f2bf(d);
;           }
;         }
;       }
;       __syncthreads();
;       f32x4 acc[8];
; #pragma unroll
;       for (int i = 0; i < 8; ++i) acc[i] = f32x4{0.f, 0.f, 0.f, 0.f};
;       const u16* wp = Wsgu + (size_t)(g * 128 + wid * 16 + fr) * 128 + fq * 8;
; #pragma unroll
;       for (int ks = 0; ks < 4; ++ks) {
;         bf16x8 af = *(const bf16x8*)(wp + ks * 32);
; #pragma unroll
;         for (int ns = 0; ns < 8; ++ns) {
;           bf16x8 bfr = *(const bf16x8*)(vT + (ns * 16 + fr) * 136 + ks * 32 + fq * 8);
;           acc[ns] = MFMA16(bfr, af, acc[ns]);
;         }
;       }
	v_lshlrev_b32_e32 v10, 16, v148
	v_and_b32_e32 v2, 0xffff0000, v148
	v_sub_f32_e32 v10, v10, v0
	v_sub_f32_e32 v2, v2, v0
	v_mul_f32_e32 v10, v1, v10
	v_mul_f32_e32 v2, v1, v2
	v_fma_f32 v10, v54, v10, v112
	v_fma_f32 v2, v55, v2, v113
	v_cvt_pk_bf16_f32 v10, v10, s0
	v_cvt_pk_bf16_f32 v2, v2, s0
	ds_write_b16 v90, v10
	ds_write_b16 v91, v2 offset:272
	v_lshlrev_b32_e32 v2, 16, v149
	v_sub_f32_e32 v2, v2, v0
	v_and_b32_e32 v3, 0xffff0000, v149
	v_mul_f32_e32 v2, v1, v2
	v_sub_f32_e32 v3, v3, v0
	v_fma_f32 v2, v2, v56, v114
	v_mul_f32_e32 v3, v1, v3
	v_fmac_f32_e32 v115, v3, v57
	v_cvt_pk_bf16_f32 v2, v2, s0
	ds_write_b16 v92, v2
	v_cvt_pk_bf16_f32 v2, v115, s0
	ds_write_b16 v93, v2 offset:272
	v_lshlrev_b32_e32 v2, 16, v150
	v_sub_f32_e32 v2, v2, v0
	v_and_b32_e32 v3, 0xffff0000, v150
	v_mul_f32_e32 v2, v1, v2
	v_sub_f32_e32 v3, v3, v0
	v_fma_f32 v2, v2, v6, v108
	v_mul_f32_e32 v3, v1, v3
	v_fma_f32 v3, v3, v7, v109
	v_cvt_pk_bf16_f32 v2, v2, s0
	ds_write_b16 v94, v2
	v_cvt_pk_bf16_f32 v2, v3, s0
	ds_write_b16 v95, v2 offset:272
	v_lshlrev_b32_e32 v2, 16, v151
	v_sub_f32_e32 v2, v2, v0
	v_and_b32_e32 v3, 0xffff0000, v151
	v_mul_f32_e32 v2, v1, v2
	v_sub_f32_e32 v0, v3, v0
	v_fma_f32 v2, v2, v8, v110
	v_mul_f32_e32 v0, v1, v0
	v_fmac_f32_e32 v111, v0, v9
	v_cvt_pk_bf16_f32 v0, v2, s0
	ds_write_b16 v96, v0
	v_cvt_pk_bf16_f32 v0, v111, s0
	ds_write_b16 v97, v0 offset:272
	v_lshlrev_b64 v[0:1], 8, v[52:53]
	v_lshl_add_u64 v[0:1], v[12:13], 0, v[0:1]
	v_mov_b32_e32 v4, v150
	v_mov_b32_e32 v5, v151
	s_waitcnt lgkmcnt(0)
	s_barrier
	global_load_dwordx4 v[152:155], v[0:1], off
	global_load_dwordx4 v[156:159], v[0:1], off offset:64
	global_load_dwordx4 v[160:163], v[0:1], off offset:128
	global_load_dwordx4 v[164:167], v[0:1], off offset:192
	ds_read_b128 v[6:9], v98
	ds_read_b128 v[54:57], v98 offset:4352
	ds_read_b128 v[58:61], v98 offset:8704
	ds_read_b128 v[104:107], v98 offset:13056
	ds_read_b128 v[108:111], v98 offset:17408
	ds_read_b128 v[112:115], v98 offset:21760
	ds_read_b128 v[116:119], v98 offset:26112
	ds_read_b128 v[120:123], v98 offset:30464
	s_waitcnt vmcnt(3) lgkmcnt(0)
	v_mfma_f32_16x16x32_bf16 v[6:9], v[6:9], v[152:155], 0
	ds_read_b128 v[124:127], v98 offset:64
	v_mfma_f32_16x16x32_bf16 v[54:57], v[54:57], v[152:155], 0
	v_mfma_f32_16x16x32_bf16 v[58:61], v[58:61], v[152:155], 0
	v_mfma_f32_16x16x32_bf16 v[104:107], v[104:107], v[152:155], 0
	v_mfma_f32_16x16x32_bf16 v[108:111], v[108:111], v[152:155], 0
	v_mfma_f32_16x16x32_bf16 v[112:115], v[112:115], v[152:155], 0
	v_mfma_f32_16x16x32_bf16 v[116:119], v[116:119], v[152:155], 0
	v_mfma_f32_16x16x32_bf16 v[2:5], v[120:123], v[152:155], 0
	s_waitcnt vmcnt(2) lgkmcnt(0)
	v_mfma_f32_16x16x32_bf16 v[6:9], v[124:127], v[156:159], v[6:9]
	ds_read_b128 v[124:127], v98 offset:4416
	s_waitcnt lgkmcnt(0)
	v_mfma_f32_16x16x32_bf16 v[54:57], v[124:127], v[156:159], v[54:57]
	ds_read_b128 v[124:127], v98 offset:8768
	s_waitcnt lgkmcnt(0)
	v_mfma_f32_16x16x32_bf16 v[58:61], v[124:127], v[156:159], v[58:61]
	ds_read_b128 v[124:127], v98 offset:13120
	s_waitcnt lgkmcnt(0)
	v_mfma_f32_16x16x32_bf16 v[104:107], v[124:127], v[156:159], v[104:107]
	ds_read_b128 v[124:127], v98 offset:17472
	s_waitcnt lgkmcnt(0)
	v_mfma_f32_16x16x32_bf16 v[108:111], v[124:127], v[156:159], v[108:111]
	ds_read_b128 v[124:127], v98 offset:21824
	s_waitcnt lgkmcnt(0)
	v_mfma_f32_16x16x32_bf16 v[112:115], v[124:127], v[156:159], v[112:115]
	ds_read_b128 v[124:127], v98 offset:26176
	s_waitcnt lgkmcnt(0)
	v_mfma_f32_16x16x32_bf16 v[116:119], v[124:127], v[156:159], v[116:119]
	ds_read_b128 v[124:127], v98 offset:30528
	s_waitcnt lgkmcnt(0)
	v_mfma_f32_16x16x32_bf16 v[2:5], v[124:127], v[156:159], v[2:5]
	ds_read_b128 v[124:127], v98 offset:128
	s_waitcnt vmcnt(1) lgkmcnt(0)
	v_mfma_f32_16x16x32_bf16 v[6:9], v[124:127], v[160:163], v[6:9]
	ds_read_b128 v[124:127], v98 offset:4480
	s_waitcnt lgkmcnt(0)
	v_mfma_f32_16x16x32_bf16 v[54:57], v[124:127], v[160:163], v[54:57]
	ds_read_b128 v[124:127], v98 offset:8832
	s_waitcnt lgkmcnt(0)
	v_mfma_f32_16x16x32_bf16 v[58:61], v[124:127], v[160:163], v[58:61]
	ds_read_b128 v[124:127], v98 offset:13184
	s_waitcnt lgkmcnt(0)
	v_mfma_f32_16x16x32_bf16 v[104:107], v[124:127], v[160:163], v[104:107]
	ds_read_b128 v[124:127], v98 offset:17536
	s_waitcnt lgkmcnt(0)
	v_mfma_f32_16x16x32_bf16 v[108:111], v[124:127], v[160:163], v[108:111]
	ds_read_b128 v[124:127], v98 offset:21888
	s_waitcnt lgkmcnt(0)
	v_mfma_f32_16x16x32_bf16 v[112:115], v[124:127], v[160:163], v[112:115]
	ds_read_b128 v[124:127], v98 offset:26240
	s_waitcnt lgkmcnt(0)
	v_mfma_f32_16x16x32_bf16 v[116:119], v[124:127], v[160:163], v[116:119]
	ds_read_b128 v[124:127], v98 offset:30592
	s_waitcnt lgkmcnt(0)
	v_mfma_f32_16x16x32_bf16 v[2:5], v[124:127], v[160:163], v[2:5]
	ds_read_b128 v[124:127], v98 offset:192
	s_waitcnt vmcnt(0) lgkmcnt(0)
	v_mfma_f32_16x16x32_bf16 v[6:9], v[124:127], v[164:167], v[6:9]
	ds_read_b128 v[124:127], v98 offset:4544
	s_waitcnt lgkmcnt(0)
	v_mfma_f32_16x16x32_bf16 v[54:57], v[124:127], v[164:167], v[54:57]
	ds_read_b128 v[124:127], v98 offset:8896
	s_waitcnt lgkmcnt(0)
	v_mfma_f32_16x16x32_bf16 v[58:61], v[124:127], v[164:167], v[58:61]
	ds_read_b128 v[124:127], v98 offset:13248
	s_waitcnt lgkmcnt(0)
	v_mfma_f32_16x16x32_bf16 v[104:107], v[124:127], v[164:167], v[104:107]
	ds_read_b128 v[124:127], v98 offset:17600
	s_waitcnt lgkmcnt(0)
	v_mfma_f32_16x16x32_bf16 v[108:111], v[124:127], v[164:167], v[108:111]
	ds_read_b128 v[124:127], v98 offset:21952
	s_waitcnt lgkmcnt(0)
	v_mfma_f32_16x16x32_bf16 v[112:115], v[124:127], v[164:167], v[112:115]
	ds_read_b128 v[124:127], v98 offset:26304
	s_waitcnt lgkmcnt(0)
; #define MFMA16(a, b, c) __builtin_amdgcn_mfma_f32_16x16x32_bf16((a), (b), (c), 0, 0, 0)
;     ...
;           acc[ns] = MFMA16(bfr, af, acc[ns]);
;         }
;       }
;       {
;         const int tl = wid * 16 + fr;
;         const float bias = sb[g * 128 + tl];
;         float* mx = (float*)(shm + 36864);
; #pragma unroll
;         for (int ns = 0; ns < 8; ++ns) {
;           f32x4 v = acc[ns];
;           v[0] += bias; v[1] += bias; v[2] += bias; v[3] += bias;
;           *(f32x4*)(mx + tl * 132 + ns * 16 + fq * 4) = v;
;         }
;       }
;       __syncthreads();
	v_mfma_f32_16x16x32_bf16 v[116:119], v[124:127], v[164:167], v[116:119]
	ds_read_b128 v[124:127], v98 offset:30656
	s_waitcnt lgkmcnt(0)
	v_mfma_f32_16x16x32_bf16 v[0:3], v[124:127], v[164:167], v[2:5]
	v_mov_b32_e32 v120, v164
	v_mov_b32_e32 v121, v165
	v_mov_b32_e32 v122, v166
	v_mov_b32_e32 v123, v167
	s_nop 2
	v_lshl_add_u64 v[4:5], v[52:53], 2, s[14:15]
	global_load_dword v10, v[4:5], off
	v_add_u32_e32 v52, 0x80, v52
	s_waitcnt vmcnt(0)
	v_pk_add_f32 v[8:9], v[8:9], v[10:11] op_sel_hi:[1,0]
	v_pk_add_f32 v[6:7], v[6:7], v[10:11] op_sel_hi:[1,0]
	ds_write_b128 v99, v[6:9] offset:36864
	v_pk_add_f32 v[6:7], v[56:57], v[10:11] op_sel_hi:[1,0]
	v_pk_add_f32 v[4:5], v[54:55], v[10:11] op_sel_hi:[1,0]
	ds_write_b128 v99, v[4:7] offset:36928
	v_pk_add_f32 v[6:7], v[60:61], v[10:11] op_sel_hi:[1,0]
	v_pk_add_f32 v[4:5], v[58:59], v[10:11] op_sel_hi:[1,0]
	ds_write_b128 v99, v[4:7] offset:36992
	v_pk_add_f32 v[6:7], v[106:107], v[10:11] op_sel_hi:[1,0]
	v_pk_add_f32 v[4:5], v[104:105], v[10:11] op_sel_hi:[1,0]
	ds_write_b128 v99, v[4:7] offset:37056
	v_pk_add_f32 v[6:7], v[110:111], v[10:11] op_sel_hi:[1,0]
	v_pk_add_f32 v[4:5], v[108:109], v[10:11] op_sel_hi:[1,0]
	ds_write_b128 v99, v[4:7] offset:37120
	v_pk_add_f32 v[6:7], v[114:115], v[10:11] op_sel_hi:[1,0]
	v_pk_add_f32 v[4:5], v[112:113], v[10:11] op_sel_hi:[1,0]
	ds_write_b128 v99, v[4:7] offset:37184
	v_pk_add_f32 v[6:7], v[118:119], v[10:11] op_sel_hi:[1,0]
	v_pk_add_f32 v[4:5], v[116:117], v[10:11] op_sel_hi:[1,0]
	v_pk_add_f32 v[2:3], v[10:11], v[2:3] op_sel_hi:[0,1]
	v_pk_add_f32 v[0:1], v[10:11], v[0:1] op_sel_hi:[0,1]
	v_lshl_add_u64 v[8:9], s[18:19], 0, v[34:35]
	ds_write_b128 v99, v[4:7] offset:37248
	ds_write_b128 v99, v[0:3] offset:37312
	s_waitcnt lgkmcnt(0)
	s_barrier
; DI float bflo(unsigned v) { return __uint_as_float(v << 16); }
; DI float bfhi(unsigned v) { return __uint_as_float(v & 0xffff0000u); }
;     ...
;       {
;         const float* mx = (const float*)(shm + 36864);
; #pragma unroll
;         for (int i = 0; i < 4; ++i) {
;           const int chunk = tid + i * 512, tl = chunk >> 4, c8 = (chunk & 15) * 8, tt = T0 + tl;
;           const f32x4 m0 = *(const f32x4*)(mx + tl * 132 + c8), m1 = *(const f32x4*)(mx + tl * 132 + c8 + 4);
;           const i32x4 u = *(const i32x4*)(projA + (size_t)tt * 1024 + g * 128 + c8);
;           u16* d = actA + (size_t)tt * 512 + g * 128 + c8;
;           const i32x4 zg = *(const i32x4*)d;
;           i32x4 o;
;           o[0] = (int)pack2(bflo((unsigned)u[0]) * m0[0] * bflo((unsigned)zg[0]), bfhi((unsigned)u[0]) * m0[1] * bfhi((unsigned)zg[0]));
;           o[1] = (int)pack2(bflo((unsigned)u[1]) * m0[2] * bflo((unsigned)zg[1]), bfhi((unsigned)u[1]) * m0[3] * bfhi((unsigned)zg[1]));
;           o[2] = (int)pack2(bflo((unsigned)u[2]) * m1[0] * bflo((unsigned)zg[2]), bfhi((unsigned)u[2]) * m1[1] * bfhi((unsigned)zg[2]));
;           o[3] = (int)pack2(bflo((unsigned)u[3]) * m1[2] * bflo((unsigned)zg[3]), bfhi((unsigned)u[3]) * m1[3] * bfhi((unsigned)zg[3]));
;           if (!dry) *(i32x4*)d = o;
;         }
;       }
	v_lshl_add_u64 v[8:9], s[18:19], 0, v[34:35]
	global_load_dwordx4 v[144:147], v[8:9], off
	v_lshl_add_u64 v[8:9], s[18:19], 0, v[36:37]
	global_load_dwordx4 v[148:151], v[8:9], off
	v_lshl_add_u64 v[8:9], s[18:19], 0, v[38:39]
	global_load_dwordx4 v[152:155], v[8:9], off
	v_lshl_add_u64 v[8:9], s[18:19], 0, v[40:41]
	global_load_dwordx4 v[156:159], v[8:9], off
	v_lshl_add_u64 v[136:137], s[18:19], 0, v[50:51]
	global_load_dwordx4 v[160:163], v[136:137], off
	v_lshl_add_u64 v[138:139], s[18:19], 0, v[48:49]
	global_load_dwordx4 v[164:167], v[138:139], off
	v_lshl_add_u64 v[140:141], s[18:19], 0, v[46:47]
	global_load_dwordx4 v[168:171], v[140:141], off
	v_lshl_add_u64 v[142:143], s[18:19], 0, v[44:45]
	global_load_dwordx4 v[172:175], v[142:143], off
	ds_read_b128 v[176:179], v100 offset:36864
	ds_read_b128 v[192:195], v100 offset:36880
	ds_read_b128 v[180:183], v101 offset:36864
	ds_read_b128 v[196:199], v101 offset:36880
	ds_read_b128 v[184:187], v102 offset:36864
	ds_read_b128 v[0:3], v102 offset:36880
	ds_read_b128 v[188:191], v103 offset:36864
	ds_read_b128 v[4:7], v103 offset:36880
	s_waitcnt vmcnt(3) lgkmcnt(6)
	v_lshlrev_b32_e32 v10, 16, v144
	v_and_b32_e32 v11, 0xffff0000, v144
	v_pk_mul_f32 v[176:177], v[176:177], v[10:11]
	v_lshlrev_b32_e32 v54, 16, v160
	v_and_b32_e32 v55, 0xffff0000, v160
	v_pk_mul_f32 v[176:177], v[176:177], v[54:55]
	s_nop 0
	v_cvt_pk_bf16_f32 v144, v176, v177
	v_lshlrev_b32_e32 v10, 16, v145
	v_and_b32_e32 v11, 0xffff0000, v145
	v_pk_mul_f32 v[178:179], v[178:179], v[10:11]
	v_lshlrev_b32_e32 v54, 16, v161
	v_and_b32_e32 v55, 0xffff0000, v161
	v_pk_mul_f32 v[178:179], v[178:179], v[54:55]
	s_nop 0
	v_cvt_pk_bf16_f32 v145, v178, v179
	v_lshlrev_b32_e32 v10, 16, v146
	v_and_b32_e32 v11, 0xffff0000, v146
	v_pk_mul_f32 v[192:193], v[192:193], v[10:11]
	v_lshlrev_b32_e32 v54, 16, v162
	v_and_b32_e32 v55, 0xffff0000, v162
	v_pk_mul_f32 v[192:193], v[192:193], v[54:55]
	s_nop 0
	v_cvt_pk_bf16_f32 v146, v192, v193
	v_lshlrev_b32_e32 v10, 16, v147
	v_and_b32_e32 v11, 0xffff0000, v147
	v_pk_mul_f32 v[194:195], v[194:195], v[10:11]
	v_lshlrev_b32_e32 v54, 16, v163
	v_and_b32_e32 v55, 0xffff0000, v163
	v_pk_mul_f32 v[194:195], v[194:195], v[54:55]
	s_nop 0
	v_cvt_pk_bf16_f32 v147, v194, v195
	s_nop 0
	global_store_dwordx4 v[136:137], v[144:147], off
	s_waitcnt vmcnt(3) lgkmcnt(4)
	v_lshlrev_b32_e32 v10, 16, v148
	v_and_b32_e32 v11, 0xffff0000, v148
	v_pk_mul_f32 v[180:181], v[180:181], v[10:11]
	v_lshlrev_b32_e32 v54, 16, v164
	v_and_b32_e32 v55, 0xffff0000, v164
	v_pk_mul_f32 v[180:181], v[180:181], v[54:55]
	s_nop 0
	v_cvt_pk_bf16_f32 v148, v180, v181
	v_lshlrev_b32_e32 v10, 16, v149
	v_and_b32_e32 v11, 0xffff0000, v149
	v_pk_mul_f32 v[182:183], v[182:183], v[10:11]
	v_lshlrev_b32_e32 v54, 16, v165
	v_and_b32_e32 v55, 0xffff0000, v165
	v_pk_mul_f32 v[182:183], v[182:183], v[54:55]
	s_nop 0
	v_cvt_pk_bf16_f32 v149, v182, v183
	v_lshlrev_b32_e32 v10, 16, v150
	v_and_b32_e32 v11, 0xffff0000, v150
	v_pk_mul_f32 v[196:197], v[196:197], v[10:11]
	v_lshlrev_b32_e32 v54, 16, v166
	v_and_b32_e32 v55, 0xffff0000, v166
	v_pk_mul_f32 v[196:197], v[196:197], v[54:55]
	s_nop 0
	v_cvt_pk_bf16_f32 v150, v196, v197
	v_lshlrev_b32_e32 v10, 16, v151
	v_and_b32_e32 v11, 0xffff0000, v151
	v_pk_mul_f32 v[198:199], v[198:199], v[10:11]
	v_lshlrev_b32_e32 v54, 16, v167
	v_and_b32_e32 v55, 0xffff0000, v167
	v_pk_mul_f32 v[198:199], v[198:199], v[54:55]
	s_nop 0
	v_cvt_pk_bf16_f32 v151, v198, v199
	s_nop 0
	global_store_dwordx4 v[138:139], v[148:151], off
	s_waitcnt vmcnt(3) lgkmcnt(2)
	v_lshlrev_b32_e32 v10, 16, v152
	v_and_b32_e32 v11, 0xffff0000, v152
	v_pk_mul_f32 v[184:185], v[184:185], v[10:11]
	v_lshlrev_b32_e32 v54, 16, v168
	v_and_b32_e32 v55, 0xffff0000, v168
	v_pk_mul_f32 v[184:185], v[184:185], v[54:55]
	s_nop 0
	v_cvt_pk_bf16_f32 v152, v184, v185
	v_lshlrev_b32_e32 v10, 16, v153
	v_and_b32_e32 v11, 0xffff0000, v153
	v_pk_mul_f32 v[186:187], v[186:187], v[10:11]
	v_lshlrev_b32_e32 v54, 16, v169
	v_and_b32_e32 v55, 0xffff0000, v169
	v_pk_mul_f32 v[186:187], v[186:187], v[54:55]
	s_nop 0
	v_cvt_pk_bf16_f32 v153, v186, v187
	v_lshlrev_b32_e32 v10, 16, v154
	v_and_b32_e32 v11, 0xffff0000, v154
	v_pk_mul_f32 v[0:1], v[0:1], v[10:11]
	v_lshlrev_b32_e32 v54, 16, v170
	v_and_b32_e32 v55, 0xffff0000, v170
	v_pk_mul_f32 v[0:1], v[0:1], v[54:55]
	s_nop 0
	v_cvt_pk_bf16_f32 v154, v0, v1
	v_lshlrev_b32_e32 v10, 16, v155
	v_and_b32_e32 v11, 0xffff0000, v155
	v_pk_mul_f32 v[2:3], v[2:3], v[10:11]
	v_lshlrev_b32_e32 v54, 16, v171
	v_and_b32_e32 v55, 0xffff0000, v171
	v_pk_mul_f32 v[2:3], v[2:3], v[54:55]
	s_nop 0
	v_cvt_pk_bf16_f32 v155, v2, v3
	s_nop 0
	global_store_dwordx4 v[140:141], v[152:155], off
	s_waitcnt vmcnt(3) lgkmcnt(0)
	v_lshlrev_b32_e32 v10, 16, v156
	v_and_b32_e32 v11, 0xffff0000, v156
	v_pk_mul_f32 v[188:189], v[188:189], v[10:11]
	v_lshlrev_b32_e32 v54, 16, v172
	v_and_b32_e32 v55, 0xffff0000, v172
	v_pk_mul_f32 v[188:189], v[188:189], v[54:55]
	s_nop 0
	v_cvt_pk_bf16_f32 v156, v188, v189
	v_lshlrev_b32_e32 v10, 16, v157
	v_and_b32_e32 v11, 0xffff0000, v157
	v_pk_mul_f32 v[190:191], v[190:191], v[10:11]
	v_lshlrev_b32_e32 v54, 16, v173
	v_and_b32_e32 v55, 0xffff0000, v173
	v_pk_mul_f32 v[190:191], v[190:191], v[54:55]
	s_nop 0
	v_cvt_pk_bf16_f32 v157, v190, v191
	v_lshlrev_b32_e32 v10, 16, v158
	v_and_b32_e32 v11, 0xffff0000, v158
	v_pk_mul_f32 v[4:5], v[4:5], v[10:11]
	v_lshlrev_b32_e32 v54, 16, v174
	v_and_b32_e32 v55, 0xffff0000, v174
	v_pk_mul_f32 v[4:5], v[4:5], v[54:55]
	s_nop 0
	v_cvt_pk_bf16_f32 v158, v4, v5
	v_lshlrev_b32_e32 v10, 16, v159
	v_and_b32_e32 v11, 0xffff0000, v159
	v_pk_mul_f32 v[6:7], v[6:7], v[10:11]
	v_lshlrev_b32_e32 v54, 16, v175
	v_and_b32_e32 v55, 0xffff0000, v175
	v_pk_mul_f32 v[6:7], v[6:7], v[54:55]
	s_nop 0
	v_cvt_pk_bf16_f32 v159, v6, v7
	s_nop 0
	global_store_dwordx4 v[142:143], v[156:159], off
	s_add_u32 s18, s18, 0x100
	s_addc_u32 s19, s19, 0
	s_cmpk_eq_i32 s16, 0x800
	s_waitcnt lgkmcnt(0)
	s_barrier
	s_cbranch_scc0 .LBB0_781
	s_add_i32 s4, s4, s72
	v_add_u32_e32 v16, s81, v16
	v_add_u32_e32 v18, s81, v18
	v_add_u32_e32 v20, s81, v20
	v_add_u32_e32 v22, s81, v22
	s_cmpk_gt_i32 s4, 0xff
	v_add_u32_e32 v30, s81, v30
	s_cbranch_scc0 .LBB0_778
	v_readlane_b32 s8, v253, 2
	v_readlane_b32 s50, v252, 18
	v_readlane_b32 s9, v253, 3
	v_readlane_b32 s51, v252, 19
	s_movk_i32 s42, 0xfc0
	v_readlane_b32 s46, v252, 31
	s_mov_b64 s[34:35], 0x20000
	s_mov_b64 s[36:37], 0x8000
	s_mov_b64 s[38:39], 0x18000
	v_readlane_b32 s10, v253, 4
	v_readlane_b32 s11, v253, 5
	v_readlane_b32 s12, v253, 6
	v_readlane_b32 s13, v253, 7
	v_readlane_b32 s14, v253, 8
	v_readlane_b32 s15, v253, 9
	v_readlane_b32 s16, v253, 10
	v_readlane_b32 s17, v253, 11
	v_readlane_b32 s18, v253, 12
	v_readlane_b32 s19, v253, 13
	v_readlane_b32 s20, v253, 14
	v_readlane_b32 s21, v253, 15
	v_readlane_b32 s22, v253, 16
	v_readlane_b32 s23, v253, 17

; template <int MF, int NF, bool SWAP = true>
; DI void gemm_main(f32x4 (&acc)[MF][NF], const u16* __restrict__ Ab, int lda, const u16* __restrict__ Bb, int ldb,
;                   int K, char* shm) {
;     ...
;   for (int t = 0; t < nt; ++t) {
;     const int cur = RING3 ? cur3 : (t & 1);
;     if constexpr (RING3) {
;       if (t + 2 < nt) G_STAGE(nxt3, t + 2);
;     } else {
;       if (t + 1 < nt) G_STAGE(cur ^ 1, t + 1);
;     }
;     const char* sA = shm + cur * STAGE;
;     const char* sB = sA + TILE_A;
;     if constexpr (MF == 8 && NF == 4) {
;       bf16x8 B0[4], B1[4], A0[4], A1[4], A2[4], A3[4];
;     ...
;       LDB_(B0, 0); LDA_(A0, 0, 0);
;       LDA_(A1, 0, 1); MMA_(A0, B0, 0);
;       LDB_(B1, 1); LDA_(A2, 1, 0); MMA_(A1, B0, 1);
;       LDA_(A3, 1, 1); MMA_(A2, B1, 0);
;       MMA_(A3, B1, 1);
;     ...
;       __builtin_amdgcn_sched_group_barrier(0x100, 8, 0);
; #pragma unroll
;       for (int i = 0; i < 4; ++i) { __builtin_amdgcn_sched_group_barrier(0x100, 1, 0); __builtin_amdgcn_sched_group_barrier(0x008, 4, 0); }
; #pragma unroll
;       for (int i = 0; i < 8; ++i) { __builtin_amdgcn_sched_group_barrier(0x100, 1, 0); __builtin_amdgcn_sched_group_barrier(0x008, 2, 0); }
; #pragma unroll
;       for (int i = 0; i < 4; ++i) { __builtin_amdgcn_sched_group_barrier(0x100, 1, 0); __builtin_amdgcn_sched_group_barrier(0x008, 4, 0); }
;       __builtin_amdgcn_sched_group_barrier(0x008, 16, 0);
;       __builtin_amdgcn_sched_barrier(0);
;     } else {
; #pragma unroll
;     for (int ks = 0; ks < 2; ++ks) {
;       bf16x8 Bf[NF];
; #pragma unroll
;       for (int n = 0; n < NF; ++n) Bf[n] = *(const bf16x8*)(sB + b_off + n * 2048 + ks * 1024);
;       constexpr int MG = (NF == 2 && MF == 8) ? 4 : MF;
; #pragma unroll
;       for (int mg = 0; mg < MF / MG; ++mg) {
;         bf16x8 At[MG];
; #pragma unroll
;         for (int m = 0; m < MG; ++m) At[m] = *(const bf16x8*)(sA + a_off + (mg * MG + m) * 2048 + ks * 1024);
; #pragma unroll
;         for (int m = 0; m < MG; ++m)
; #pragma unroll
;           for (int n = 0; n < NF; ++n)
;             acc[mg * MG + m][n] = SWAP ? MFMA16(Bf[n], At[m], acc[mg * MG + m][n]) : MFMA16(At[m], Bf[n], acc[mg * MG + m][n]);
;         if (mg == 0) __builtin_amdgcn_sched_group_barrier(0x100, MG + NF, 0);
;         else __builtin_amdgcn_sched_group_barrier(0x100, MG, 0);
;         __builtin_amdgcn_sched_group_barrier(0x008, MG * NF, 0);
.LBB0_920:
	s_mul_i32 s98, s28, 0xc000
	v_or_b32_e32 v69, s98, v66
	v_add_u32_e32 v94, v69, v67
	v_add_u32_e32 v69, v69, v65
	ds_read_b128 v[70:73], v94 offset:32768
	ds_read_b128 v[74:77], v94 offset:34816
	ds_read_b128 v[78:81], v69
	ds_read_b128 v[82:85], v69 offset:2048
	ds_read_b128 v[86:89], v69 offset:4096
	ds_read_b128 v[90:93], v69 offset:6144
	ds_read_b128 v[96:99], v69 offset:8192
	ds_read_b128 v[100:103], v69 offset:10240
	ds_read_b128 v[104:107], v69 offset:12288
	ds_read_b128 v[108:111], v69 offset:14336
	s_cmp_gt_u32 s27, 1
	s_cselect_b64 s[12:13], -1, 0
	s_and_b64 vcc, exec, s[12:13]
	s_cbranch_vccnz .Lppa_nodma
	s_cmp_eq_u32 s27, 0
	s_cbranch_scc1 .Lppa_first
	v_mfma_f32_16x16x32_bf16 v[60:63], v[112:115], v[120:123], v[60:63]
	v_add_u32_e32 v95, s25, v68
	s_mul_i32 s14, s26, 0xc000
	v_add_u32_e32 v130, 0x80, v95
	v_mfma_f32_16x16x32_bf16 v[56:59], v[116:119], v[120:123], v[56:59]
	v_add_u32_e32 v129, s14, v64
	v_ashrrev_i32_e32 v131, 31, v130
	v_lshlrev_b64 v[130:131], 1, v[130:131]
	v_mfma_f32_16x16x32_bf16 v[52:55], v[112:115], v[124:127], v[52:55]
	v_readfirstlane_b32 s14, v129
	v_lshl_add_u64 v[160:161], s[8:9], 0, v[130:131]
	s_mov_b32 m0, s14
	v_mfma_f32_16x16x32_bf16 v[48:51], v[116:119], v[124:127], v[48:51]
	v_add_u32_e32 v132, 0x2000, v129
	global_load_lds_dwordx4 v[160:161], off
	v_add_u32_e32 v160, 0x4080, v95
	v_mfma_f32_16x16x32_bf16 v[44:47], v[112:115], v[136:139], v[44:47]
	v_ashrrev_i32_e32 v161, 31, v160
	v_lshlrev_b64 v[160:161], 1, v[160:161]
	v_readfirstlane_b32 s14, v132
	v_mfma_f32_16x16x32_bf16 v[40:43], v[116:119], v[136:139], v[40:43]
	v_lshl_add_u64 v[162:163], s[8:9], 0, v[160:161]
	s_mov_b32 m0, s14
	v_add_u32_e32 v132, 0x4000, v129
	v_mfma_f32_16x16x32_bf16 v[36:39], v[112:115], v[140:143], v[36:39]
	global_load_lds_dwordx4 v[162:163], off
	v_add_u32_e32 v162, 0x8080, v95
	v_ashrrev_i32_e32 v163, 31, v162
	v_mfma_f32_16x16x32_bf16 v[32:35], v[116:119], v[140:143], v[32:35]
	v_readfirstlane_b32 s14, v132
	v_lshl_add_u64 v[162:163], v[162:163], 1, s[8:9]
	s_mov_b32 m0, s14
	v_mfma_f32_16x16x32_bf16 v[28:31], v[112:115], v[144:147], v[28:31]
	v_lshl_add_u64 v[130:131], s[10:11], 0, v[130:131]
	global_load_lds_dwordx4 v[162:163], off
	v_add_u32_e32 v162, 0xc080, v95
	v_mfma_f32_16x16x32_bf16 v[24:27], v[116:119], v[144:147], v[24:27]
	v_add_u32_e32 v95, 0x6000, v129
	v_ashrrev_i32_e32 v163, 31, v162
	v_readfirstlane_b32 s14, v95
	v_mfma_f32_16x16x32_bf16 v[20:23], v[112:115], v[148:151], v[20:23]
	v_lshl_add_u64 v[162:163], v[162:163], 1, s[8:9]
	s_mov_b32 m0, s14
	s_nop 0
	v_mfma_f32_16x16x32_bf16 v[16:19], v[116:119], v[148:151], v[16:19]
	global_load_lds_dwordx4 v[162:163], off
	v_add_u32_e32 v162, 0x8000, v129
	v_add_u32_e32 v129, 0xa000, v129
	v_mfma_f32_16x16x32_bf16 v[12:15], v[112:115], v[152:155], v[12:15]
	v_readfirstlane_b32 s14, v162
	s_mov_b32 m0, s14
	v_readfirstlane_b32 s14, v129
	v_mfma_f32_16x16x32_bf16 v[8:11], v[116:119], v[152:155], v[8:11]
	global_load_lds_dwordx4 v[130:131], off
	v_lshl_add_u64 v[130:131], s[10:11], 0, v[160:161]
	s_mov_b32 m0, s14
	v_mfma_f32_16x16x32_bf16 v[4:7], v[112:115], v[156:159], v[4:7]
	s_nop 0
	global_load_lds_dwordx4 v[130:131], off
	v_mfma_f32_16x16x32_bf16 v[0:3], v[116:119], v[156:159], v[0:3]
	s_branch .Lppa_main
; #define MFMA16(a, b, c) __builtin_amdgcn_mfma_f32_16x16x32_bf16((a), (b), (c), 0, 0, 0)
; template <int MF, int NF, bool SWAP = true>
; DI void gemm_main(f32x4 (&acc)[MF][NF], const u16* __restrict__ Ab, int lda, const u16* __restrict__ Bb, int ldb,
;                   int K, char* shm) {
;     ...
;     if constexpr (RING3) {
;       if (t + 2 < nt) G_STAGE(nxt3, t + 2);
;     ...
;     for (int ks = 0; ks < 2; ++ks) {
;       bf16x8 Bf[NF];
; #pragma unroll
;       for (int n = 0; n < NF; ++n) Bf[n] = *(const bf16x8*)(sB + b_off + n * 2048 + ks * 1024);
;       constexpr int MG = (NF == 2 && MF == 8) ? 4 : MF;
; #pragma unroll
;       for (int mg = 0; mg < MF / MG; ++mg) {
;         bf16x8 At[MG];
; #pragma unroll
;         for (int m = 0; m < MG; ++m) At[m] = *(const bf16x8*)(sA + a_off + (mg * MG + m) * 2048 + ks * 1024);
; #pragma unroll
;         for (int m = 0; m < MG; ++m)
; #pragma unroll
;           for (int n = 0; n < NF; ++n)
;             acc[mg * MG + m][n] = SWAP ? MFMA16(Bf[n], At[m], acc[mg * MG + m][n]) : MFMA16(At[m], Bf[n], acc[mg * MG + m][n]);
;         if (mg == 0) __builtin_amdgcn_sched_group_barrier(0x100, MG + NF, 0);
;         else __builtin_amdgcn_sched_group_barrier(0x100, MG, 0);
;         __builtin_amdgcn_sched_group_barrier(0x008, MG * NF, 0);
;         __builtin_amdgcn_sched_barrier(0);
;       }
.Lppa_first:
	v_add_u32_e32 v95, s25, v68
	s_mul_i32 s14, s26, 0xc000
	v_add_u32_e32 v130, 0x80, v95
	v_add_u32_e32 v129, s14, v64
	v_ashrrev_i32_e32 v131, 31, v130
	v_lshlrev_b64 v[130:131], 1, v[130:131]
	v_readfirstlane_b32 s14, v129
	v_lshl_add_u64 v[160:161], s[8:9], 0, v[130:131]
	s_mov_b32 m0, s14
	v_add_u32_e32 v132, 0x2000, v129
	global_load_lds_dwordx4 v[160:161], off
	v_add_u32_e32 v160, 0x4080, v95
	v_ashrrev_i32_e32 v161, 31, v160
	v_lshlrev_b64 v[160:161], 1, v[160:161]
	v_readfirstlane_b32 s14, v132
	v_lshl_add_u64 v[162:163], s[8:9], 0, v[160:161]
	s_mov_b32 m0, s14
	v_add_u32_e32 v132, 0x4000, v129
	global_load_lds_dwordx4 v[162:163], off
	v_add_u32_e32 v162, 0x8080, v95
	v_ashrrev_i32_e32 v163, 31, v162
	v_readfirstlane_b32 s14, v132
	v_lshl_add_u64 v[162:163], v[162:163], 1, s[8:9]
	s_mov_b32 m0, s14
	v_lshl_add_u64 v[130:131], s[10:11], 0, v[130:131]
	global_load_lds_dwordx4 v[162:163], off
	v_add_u32_e32 v162, 0xc080, v95
	v_add_u32_e32 v95, 0x6000, v129
	v_ashrrev_i32_e32 v163, 31, v162
	v_readfirstlane_b32 s14, v95
	v_lshl_add_u64 v[162:163], v[162:163], 1, s[8:9]
	s_mov_b32 m0, s14
	s_nop 0
	global_load_lds_dwordx4 v[162:163], off
	v_add_u32_e32 v162, 0x8000, v129
	v_add_u32_e32 v129, 0xa000, v129
	v_readfirstlane_b32 s14, v162
	s_mov_b32 m0, s14
	v_readfirstlane_b32 s14, v129
	global_load_lds_dwordx4 v[130:131], off
	v_lshl_add_u64 v[130:131], s[10:11], 0, v[160:161]
	s_mov_b32 m0, s14
	s_nop 0
	global_load_lds_dwordx4 v[130:131], off
	s_branch .Lppa_main
.Lppa_nodma:
	v_mfma_f32_16x16x32_bf16 v[60:63], v[112:115], v[120:123], v[60:63]
	v_mfma_f32_16x16x32_bf16 v[56:59], v[116:119], v[120:123], v[56:59]
	v_mfma_f32_16x16x32_bf16 v[52:55], v[112:115], v[124:127], v[52:55]
	v_mfma_f32_16x16x32_bf16 v[48:51], v[116:119], v[124:127], v[48:51]
	v_mfma_f32_16x16x32_bf16 v[44:47], v[112:115], v[136:139], v[44:47]
	v_mfma_f32_16x16x32_bf16 v[40:43], v[116:119], v[136:139], v[40:43]
	v_mfma_f32_16x16x32_bf16 v[36:39], v[112:115], v[140:143], v[36:39]
	v_mfma_f32_16x16x32_bf16 v[32:35], v[116:119], v[140:143], v[32:35]
	v_mfma_f32_16x16x32_bf16 v[28:31], v[112:115], v[144:147], v[28:31]
	v_mfma_f32_16x16x32_bf16 v[24:27], v[116:119], v[144:147], v[24:27]
	v_mfma_f32_16x16x32_bf16 v[20:23], v[112:115], v[148:151], v[20:23]
	v_mfma_f32_16x16x32_bf16 v[16:19], v[116:119], v[148:151], v[16:19]
	v_mfma_f32_16x16x32_bf16 v[12:15], v[112:115], v[152:155], v[12:15]
	v_mfma_f32_16x16x32_bf16 v[8:11], v[116:119], v[152:155], v[8:11]
	v_mfma_f32_16x16x32_bf16 v[4:7], v[112:115], v[156:159], v[4:7]
	v_mfma_f32_16x16x32_bf16 v[0:3], v[116:119], v[156:159], v[0:3]
.Lppa_main:
	s_waitcnt lgkmcnt(7)
	v_mfma_f32_16x16x32_bf16 v[60:63], v[70:73], v[78:81], v[60:63]
	ds_read_b128 v[112:115], v94 offset:33792
	v_mfma_f32_16x16x32_bf16 v[56:59], v[74:77], v[78:81], v[56:59]
	ds_read_b128 v[116:119], v94 offset:35840
	s_waitcnt lgkmcnt(8)
	v_mfma_f32_16x16x32_bf16 v[52:55], v[70:73], v[82:85], v[52:55]
	v_mfma_f32_16x16x32_bf16 v[48:51], v[74:77], v[82:85], v[48:51]
	ds_read_b128 v[120:123], v69 offset:1024
	s_waitcnt lgkmcnt(8)
	v_mfma_f32_16x16x32_bf16 v[44:47], v[70:73], v[86:89], v[44:47]
	ds_read_b128 v[124:127], v69 offset:3072
	v_mfma_f32_16x16x32_bf16 v[40:43], v[74:77], v[86:89], v[40:43]
	s_waitcnt lgkmcnt(8)
	v_mfma_f32_16x16x32_bf16 v[36:39], v[70:73], v[90:93], v[36:39]
	ds_read_b128 v[136:139], v69 offset:5120
	v_mfma_f32_16x16x32_bf16 v[32:35], v[74:77], v[90:93], v[32:35]
	ds_read_b128 v[140:143], v69 offset:7168
	s_waitcnt lgkmcnt(9)
	v_mfma_f32_16x16x32_bf16 v[28:31], v[70:73], v[96:99], v[28:31]
	v_mfma_f32_16x16x32_bf16 v[24:27], v[74:77], v[96:99], v[24:27]
	ds_read_b128 v[144:147], v69 offset:9216
	s_waitcnt lgkmcnt(9)
	v_mfma_f32_16x16x32_bf16 v[20:23], v[70:73], v[100:103], v[20:23]
	ds_read_b128 v[148:151], v69 offset:11264
	v_mfma_f32_16x16x32_bf16 v[16:19], v[74:77], v[100:103], v[16:19]
	s_waitcnt lgkmcnt(9)
	v_mfma_f32_16x16x32_bf16 v[12:15], v[70:73], v[104:107], v[12:15]
	ds_read_b128 v[152:155], v69 offset:13312
	v_mfma_f32_16x16x32_bf16 v[8:11], v[74:77], v[104:107], v[8:11]
	ds_read_b128 v[156:159], v69 offset:15360
	s_waitcnt lgkmcnt(10)
	v_mfma_f32_16x16x32_bf16 v[4:7], v[70:73], v[108:111], v[4:7]
	v_mfma_f32_16x16x32_bf16 v[0:3], v[74:77], v[108:111], v[0:3]
	s_waitcnt lgkmcnt(0)
	s_mov_b64 s[14:15], -1
	s_and_b64 vcc, exec, s[12:13]
	s_cbranch_vccz .LBB0_924
	s_waitcnt vmcnt(0)
	s_mov_b64 s[14:15], 0

; #define MFMA16(a, b, c) __builtin_amdgcn_mfma_f32_16x16x32_bf16((a), (b), (c), 0, 0, 0)
; template <int MF, int NF, bool SWAP = true>
; DI void gemm_main(f32x4 (&acc)[MF][NF], const u16* __restrict__ Ab, int lda, const u16* __restrict__ Bb, int ldb,
;                   int K, char* shm) {
;     ...
;     for (int ks = 0; ks < 2; ++ks) {
;       bf16x8 Bf[NF];
; #pragma unroll
;       for (int n = 0; n < NF; ++n) Bf[n] = *(const bf16x8*)(sB + b_off + n * 2048 + ks * 1024);
;       constexpr int MG = (NF == 2 && MF == 8) ? 4 : MF;
; #pragma unroll
;       for (int mg = 0; mg < MF / MG; ++mg) {
;         bf16x8 At[MG];
; #pragma unroll
;         for (int m = 0; m < MG; ++m) At[m] = *(const bf16x8*)(sA + a_off + (mg * MG + m) * 2048 + ks * 1024);
; #pragma unroll
;         for (int m = 0; m < MG; ++m)
; #pragma unroll
;           for (int n = 0; n < NF; ++n)
;             acc[mg * MG + m][n] = SWAP ? MFMA16(Bf[n], At[m], acc[mg * MG + m][n]) : MFMA16(At[m], Bf[n], acc[mg * MG + m][n]);
.Lppa_exit:
	v_mfma_f32_16x16x32_bf16 v[60:63], v[112:115], v[120:123], v[60:63]
	v_mfma_f32_16x16x32_bf16 v[56:59], v[116:119], v[120:123], v[56:59]
	v_mfma_f32_16x16x32_bf16 v[52:55], v[112:115], v[124:127], v[52:55]
	v_mfma_f32_16x16x32_bf16 v[48:51], v[116:119], v[124:127], v[48:51]
	v_mfma_f32_16x16x32_bf16 v[44:47], v[112:115], v[136:139], v[44:47]
	v_mfma_f32_16x16x32_bf16 v[40:43], v[116:119], v[136:139], v[40:43]
	v_mfma_f32_16x16x32_bf16 v[36:39], v[112:115], v[140:143], v[36:39]
	v_mfma_f32_16x16x32_bf16 v[32:35], v[116:119], v[140:143], v[32:35]
	v_mfma_f32_16x16x32_bf16 v[28:31], v[112:115], v[144:147], v[28:31]
	v_mfma_f32_16x16x32_bf16 v[24:27], v[116:119], v[144:147], v[24:27]
	v_mfma_f32_16x16x32_bf16 v[20:23], v[112:115], v[148:151], v[20:23]
	v_mfma_f32_16x16x32_bf16 v[16:19], v[116:119], v[148:151], v[16:19]
	v_mfma_f32_16x16x32_bf16 v[12:15], v[112:115], v[152:155], v[12:15]
	v_mfma_f32_16x16x32_bf16 v[8:11], v[116:119], v[152:155], v[8:11]
	v_mfma_f32_16x16x32_bf16 v[4:7], v[112:115], v[156:159], v[4:7]
	v_mfma_f32_16x16x32_bf16 v[0:3], v[116:119], v[156:159], v[0:3]
	s_nop 7
	s_nop 1
	s_branch .LBB0_926

; template <int MF, int NF, bool SWAP = true>
; DI void gemm_main(f32x4 (&acc)[MF][NF], const u16* __restrict__ Ab, int lda, const u16* __restrict__ Bb, int ldb,
;                   int K, char* shm) {
;     ...
;   for (int t = 0; t < nt; ++t) {
;     const int cur = RING3 ? cur3 : (t & 1);
;     if constexpr (RING3) {
;       if (t + 2 < nt) G_STAGE(nxt3, t + 2);
;     } else {
;       if (t + 1 < nt) G_STAGE(cur ^ 1, t + 1);
;     }
;     const char* sA = shm + cur * STAGE;
;     const char* sB = sA + TILE_A;
;     if constexpr (MF == 8 && NF == 4) {
;       bf16x8 B0[4], B1[4], A0[4], A1[4], A2[4], A3[4];
;     ...
;       LDB_(B0, 0); LDA_(A0, 0, 0);
;       LDA_(A1, 0, 1); MMA_(A0, B0, 0);
;       LDB_(B1, 1); LDA_(A2, 1, 0); MMA_(A1, B0, 1);
;       LDA_(A3, 1, 1); MMA_(A2, B1, 0);
;       MMA_(A3, B1, 1);
;     ...
;       __builtin_amdgcn_sched_group_barrier(0x100, 8, 0);
; #pragma unroll
;       for (int i = 0; i < 4; ++i) { __builtin_amdgcn_sched_group_barrier(0x100, 1, 0); __builtin_amdgcn_sched_group_barrier(0x008, 4, 0); }
; #pragma unroll
;       for (int i = 0; i < 8; ++i) { __builtin_amdgcn_sched_group_barrier(0x100, 1, 0); __builtin_amdgcn_sched_group_barrier(0x008, 2, 0); }
; #pragma unroll
;       for (int i = 0; i < 4; ++i) { __builtin_amdgcn_sched_group_barrier(0x100, 1, 0); __builtin_amdgcn_sched_group_barrier(0x008, 4, 0); }
;       __builtin_amdgcn_sched_group_barrier(0x008, 16, 0);
;       __builtin_amdgcn_sched_barrier(0);
;     } else {
; #pragma unroll
;     for (int ks = 0; ks < 2; ++ks) {
;       bf16x8 Bf[NF];
; #pragma unroll
;       for (int n = 0; n < NF; ++n) Bf[n] = *(const bf16x8*)(sB + b_off + n * 2048 + ks * 1024);
;       constexpr int MG = (NF == 2 && MF == 8) ? 4 : MF;
; #pragma unroll
;       for (int mg = 0; mg < MF / MG; ++mg) {
;         bf16x8 At[MG];
; #pragma unroll
;         for (int m = 0; m < MG; ++m) At[m] = *(const bf16x8*)(sA + a_off + (mg * MG + m) * 2048 + ks * 1024);
; #pragma unroll
;         for (int m = 0; m < MG; ++m)
; #pragma unroll
;           for (int n = 0; n < NF; ++n)
;             acc[mg * MG + m][n] = SWAP ? MFMA16(Bf[n], At[m], acc[mg * MG + m][n]) : MFMA16(At[m], Bf[n], acc[mg * MG + m][n]);
;         if (mg == 0) __builtin_amdgcn_sched_group_barrier(0x100, MG + NF, 0);
;         else __builtin_amdgcn_sched_group_barrier(0x100, MG, 0);
;         __builtin_amdgcn_sched_group_barrier(0x008, MG * NF, 0);
.LBB0_928:
	s_mul_i32 s98, s27, 0xc000
	v_or_b32_e32 v137, s98, v131
	v_add_u32_e32 v162, v137, v132
	v_add_u32_e32 v137, v137, v130
	ds_read_b128 v[138:141], v162 offset:32768
	ds_read_b128 v[142:145], v162 offset:34816
	ds_read_b128 v[146:149], v137
	ds_read_b128 v[150:153], v137 offset:2048
	ds_read_b128 v[154:157], v137 offset:4096
	ds_read_b128 v[158:161], v137 offset:6144
	ds_read_b128 v[164:167], v137 offset:8192
	ds_read_b128 v[168:171], v137 offset:10240
	ds_read_b128 v[172:175], v137 offset:12288
	ds_read_b128 v[176:179], v137 offset:14336
	s_cmp_gt_u32 s26, 13
	s_cselect_b64 s[12:13], -1, 0
	s_and_b64 vcc, exec, s[12:13]
	s_cbranch_vccnz .Lppb_nodma
	s_cmp_eq_u32 s26, 0
	s_cbranch_scc1 .Lppb_first
	v_mfma_f32_16x16x32_bf16 v[124:127], v[180:183], v[188:191], v[124:127]
	v_add_u32_e32 v163, s25, v136
	s_mul_i32 s14, s5, 0xc000
	v_add_u32_e32 v200, 0x80, v163
	v_mfma_f32_16x16x32_bf16 v[120:123], v[184:187], v[188:191], v[120:123]
	v_add_u32_e32 v211, s14, v129
	v_ashrrev_i32_e32 v201, 31, v200
	v_lshlrev_b64 v[200:201], 1, v[200:201]
	v_mfma_f32_16x16x32_bf16 v[116:119], v[180:183], v[192:195], v[116:119]
	v_readfirstlane_b32 s14, v211
	v_lshl_add_u64 v[232:233], s[8:9], 0, v[200:201]
	s_mov_b32 m0, s14
	v_mfma_f32_16x16x32_bf16 v[112:115], v[184:187], v[192:195], v[112:115]
	v_add_u32_e32 v236, 0x2000, v211
	global_load_lds_dwordx4 v[232:233], off
	v_add_u32_e32 v232, 0x10080, v163
	v_mfma_f32_16x16x32_bf16 v[108:111], v[180:183], v[196:199], v[108:111]
	v_ashrrev_i32_e32 v233, 31, v232
	v_lshlrev_b64 v[232:233], 1, v[232:233]
	v_readfirstlane_b32 s14, v236
	v_mfma_f32_16x16x32_bf16 v[104:107], v[184:187], v[196:199], v[104:107]
	v_lshl_add_u64 v[234:235], s[8:9], 0, v[232:233]
	s_mov_b32 m0, s14
	v_add_u32_e32 v236, 0x4000, v211
	v_mfma_f32_16x16x32_bf16 v[100:103], v[180:183], v[212:215], v[100:103]
	global_load_lds_dwordx4 v[234:235], off
	v_add_u32_e32 v234, 0x20080, v163
	v_ashrrev_i32_e32 v235, 31, v234
	v_mfma_f32_16x16x32_bf16 v[96:99], v[184:187], v[212:215], v[96:99]
	v_readfirstlane_b32 s14, v236
	v_lshl_add_u64 v[234:235], v[234:235], 1, s[8:9]
	s_mov_b32 m0, s14
	v_mfma_f32_16x16x32_bf16 v[92:95], v[180:183], v[216:219], v[92:95]
	v_lshl_add_u64 v[200:201], s[10:11], 0, v[200:201]
	global_load_lds_dwordx4 v[234:235], off
	v_add_u32_e32 v234, 0x30080, v163
	v_mfma_f32_16x16x32_bf16 v[88:91], v[184:187], v[216:219], v[88:91]
	v_add_u32_e32 v163, 0x6000, v211
	v_ashrrev_i32_e32 v235, 31, v234
	v_readfirstlane_b32 s14, v163
	v_mfma_f32_16x16x32_bf16 v[84:87], v[180:183], v[220:223], v[84:87]
	v_lshl_add_u64 v[234:235], v[234:235], 1, s[8:9]
	s_mov_b32 m0, s14
	s_nop 0
	v_mfma_f32_16x16x32_bf16 v[80:83], v[184:187], v[220:223], v[80:83]
	global_load_lds_dwordx4 v[234:235], off
	v_add_u32_e32 v234, 0x8000, v211
	v_add_u32_e32 v211, 0xa000, v211
	v_mfma_f32_16x16x32_bf16 v[76:79], v[180:183], v[224:227], v[76:79]
	v_readfirstlane_b32 s14, v234
	s_mov_b32 m0, s14
	v_readfirstlane_b32 s14, v211
	v_mfma_f32_16x16x32_bf16 v[72:75], v[184:187], v[224:227], v[72:75]
	global_load_lds_dwordx4 v[200:201], off
	v_lshl_add_u64 v[200:201], s[10:11], 0, v[232:233]
	s_mov_b32 m0, s14
	v_mfma_f32_16x16x32_bf16 v[68:71], v[180:183], v[228:231], v[68:71]
	s_nop 0
	global_load_lds_dwordx4 v[200:201], off
	v_mfma_f32_16x16x32_bf16 v[64:67], v[184:187], v[228:231], v[64:67]
	s_branch .Lppb_main
; #define MFMA16(a, b, c) __builtin_amdgcn_mfma_f32_16x16x32_bf16((a), (b), (c), 0, 0, 0)
; template <int MF, int NF, bool SWAP = true>
; DI void gemm_main(f32x4 (&acc)[MF][NF], const u16* __restrict__ Ab, int lda, const u16* __restrict__ Bb, int ldb,
;                   int K, char* shm) {
;     ...
;     if constexpr (RING3) {
;       if (t + 2 < nt) G_STAGE(nxt3, t + 2);
;     ...
;     for (int ks = 0; ks < 2; ++ks) {
;       bf16x8 Bf[NF];
; #pragma unroll
;       for (int n = 0; n < NF; ++n) Bf[n] = *(const bf16x8*)(sB + b_off + n * 2048 + ks * 1024);
;       constexpr int MG = (NF == 2 && MF == 8) ? 4 : MF;
; #pragma unroll
;       for (int mg = 0; mg < MF / MG; ++mg) {
;         bf16x8 At[MG];
; #pragma unroll
;         for (int m = 0; m < MG; ++m) At[m] = *(const bf16x8*)(sA + a_off + (mg * MG + m) * 2048 + ks * 1024);
; #pragma unroll
;         for (int m = 0; m < MG; ++m)
; #pragma unroll
;           for (int n = 0; n < NF; ++n)
;             acc[mg * MG + m][n] = SWAP ? MFMA16(Bf[n], At[m], acc[mg * MG + m][n]) : MFMA16(At[m], Bf[n], acc[mg * MG + m][n]);
;         if (mg == 0) __builtin_amdgcn_sched_group_barrier(0x100, MG + NF, 0);
;         else __builtin_amdgcn_sched_group_barrier(0x100, MG, 0);
;         __builtin_amdgcn_sched_group_barrier(0x008, MG * NF, 0);
;         __builtin_amdgcn_sched_barrier(0);
;       }
.Lppb_first:
	v_add_u32_e32 v163, s25, v136
	s_mul_i32 s14, s5, 0xc000
	v_add_u32_e32 v200, 0x80, v163
	v_add_u32_e32 v211, s14, v129
	v_ashrrev_i32_e32 v201, 31, v200
	v_lshlrev_b64 v[200:201], 1, v[200:201]
	v_readfirstlane_b32 s14, v211
	v_lshl_add_u64 v[232:233], s[8:9], 0, v[200:201]
	s_mov_b32 m0, s14
	v_add_u32_e32 v236, 0x2000, v211
	global_load_lds_dwordx4 v[232:233], off
	v_add_u32_e32 v232, 0x10080, v163
	v_ashrrev_i32_e32 v233, 31, v232
	v_lshlrev_b64 v[232:233], 1, v[232:233]
	v_readfirstlane_b32 s14, v236
	v_lshl_add_u64 v[234:235], s[8:9], 0, v[232:233]
	s_mov_b32 m0, s14
	v_add_u32_e32 v236, 0x4000, v211
	global_load_lds_dwordx4 v[234:235], off
	v_add_u32_e32 v234, 0x20080, v163
	v_ashrrev_i32_e32 v235, 31, v234
	v_readfirstlane_b32 s14, v236
	v_lshl_add_u64 v[234:235], v[234:235], 1, s[8:9]
	s_mov_b32 m0, s14
	v_lshl_add_u64 v[200:201], s[10:11], 0, v[200:201]
	global_load_lds_dwordx4 v[234:235], off
	v_add_u32_e32 v234, 0x30080, v163
	v_add_u32_e32 v163, 0x6000, v211
	v_ashrrev_i32_e32 v235, 31, v234
	v_readfirstlane_b32 s14, v163
	v_lshl_add_u64 v[234:235], v[234:235], 1, s[8:9]
	s_mov_b32 m0, s14
	s_nop 0
	global_load_lds_dwordx4 v[234:235], off
	v_add_u32_e32 v234, 0x8000, v211
	v_add_u32_e32 v211, 0xa000, v211
	v_readfirstlane_b32 s14, v234
	s_mov_b32 m0, s14
	v_readfirstlane_b32 s14, v211
	global_load_lds_dwordx4 v[200:201], off
	v_lshl_add_u64 v[200:201], s[10:11], 0, v[232:233]
	s_mov_b32 m0, s14
	s_nop 0
	global_load_lds_dwordx4 v[200:201], off
	s_branch .Lppb_main
.Lppb_nodma:
	v_mfma_f32_16x16x32_bf16 v[124:127], v[180:183], v[188:191], v[124:127]
	v_mfma_f32_16x16x32_bf16 v[120:123], v[184:187], v[188:191], v[120:123]
	v_mfma_f32_16x16x32_bf16 v[116:119], v[180:183], v[192:195], v[116:119]
	v_mfma_f32_16x16x32_bf16 v[112:115], v[184:187], v[192:195], v[112:115]
	v_mfma_f32_16x16x32_bf16 v[108:111], v[180:183], v[196:199], v[108:111]
	v_mfma_f32_16x16x32_bf16 v[104:107], v[184:187], v[196:199], v[104:107]
	v_mfma_f32_16x16x32_bf16 v[100:103], v[180:183], v[212:215], v[100:103]
	v_mfma_f32_16x16x32_bf16 v[96:99], v[184:187], v[212:215], v[96:99]
	v_mfma_f32_16x16x32_bf16 v[92:95], v[180:183], v[216:219], v[92:95]
	v_mfma_f32_16x16x32_bf16 v[88:91], v[184:187], v[216:219], v[88:91]
	v_mfma_f32_16x16x32_bf16 v[84:87], v[180:183], v[220:223], v[84:87]
	v_mfma_f32_16x16x32_bf16 v[80:83], v[184:187], v[220:223], v[80:83]
	v_mfma_f32_16x16x32_bf16 v[76:79], v[180:183], v[224:227], v[76:79]
	v_mfma_f32_16x16x32_bf16 v[72:75], v[184:187], v[224:227], v[72:75]
	v_mfma_f32_16x16x32_bf16 v[68:71], v[180:183], v[228:231], v[68:71]
	v_mfma_f32_16x16x32_bf16 v[64:67], v[184:187], v[228:231], v[64:67]
.Lppb_main:
	s_waitcnt lgkmcnt(7)
	v_mfma_f32_16x16x32_bf16 v[124:127], v[138:141], v[146:149], v[124:127]
	ds_read_b128 v[180:183], v162 offset:33792
	v_mfma_f32_16x16x32_bf16 v[120:123], v[142:145], v[146:149], v[120:123]
	ds_read_b128 v[184:187], v162 offset:35840
	s_waitcnt lgkmcnt(8)
	v_mfma_f32_16x16x32_bf16 v[116:119], v[138:141], v[150:153], v[116:119]
	v_mfma_f32_16x16x32_bf16 v[112:115], v[142:145], v[150:153], v[112:115]
	ds_read_b128 v[188:191], v137 offset:1024
	s_waitcnt lgkmcnt(8)
	v_mfma_f32_16x16x32_bf16 v[108:111], v[138:141], v[154:157], v[108:111]
	ds_read_b128 v[192:195], v137 offset:3072
	v_mfma_f32_16x16x32_bf16 v[104:107], v[142:145], v[154:157], v[104:107]
	s_waitcnt lgkmcnt(8)
	v_mfma_f32_16x16x32_bf16 v[100:103], v[138:141], v[158:161], v[100:103]
	ds_read_b128 v[196:199], v137 offset:5120
	v_mfma_f32_16x16x32_bf16 v[96:99], v[142:145], v[158:161], v[96:99]
	ds_read_b128 v[212:215], v137 offset:7168
	s_waitcnt lgkmcnt(9)
	v_mfma_f32_16x16x32_bf16 v[92:95], v[138:141], v[164:167], v[92:95]
	v_mfma_f32_16x16x32_bf16 v[88:91], v[142:145], v[164:167], v[88:91]
	ds_read_b128 v[216:219], v137 offset:9216
	s_waitcnt lgkmcnt(9)
	v_mfma_f32_16x16x32_bf16 v[84:87], v[138:141], v[168:171], v[84:87]
	ds_read_b128 v[220:223], v137 offset:11264
	v_mfma_f32_16x16x32_bf16 v[80:83], v[142:145], v[168:171], v[80:83]
	s_waitcnt lgkmcnt(9)
	v_mfma_f32_16x16x32_bf16 v[76:79], v[138:141], v[172:175], v[76:79]
	ds_read_b128 v[224:227], v137 offset:13312
	v_mfma_f32_16x16x32_bf16 v[72:75], v[142:145], v[172:175], v[72:75]
	ds_read_b128 v[228:231], v137 offset:15360
	s_waitcnt lgkmcnt(10)
	v_mfma_f32_16x16x32_bf16 v[68:71], v[138:141], v[176:179], v[68:71]
	v_mfma_f32_16x16x32_bf16 v[64:67], v[142:145], v[176:179], v[64:67]
	s_waitcnt lgkmcnt(0)
	s_mov_b64 s[14:15], -1
	s_and_b64 vcc, exec, s[12:13]
	s_cbranch_vccz .LBB0_932
	s_waitcnt vmcnt(0)
	s_mov_b64 s[14:15], 0

; #define MFMA16(a, b, c) __builtin_amdgcn_mfma_f32_16x16x32_bf16((a), (b), (c), 0, 0, 0)
; template <int MF, int NF, bool SWAP = true>
; DI void gemm_main(f32x4 (&acc)[MF][NF], const u16* __restrict__ Ab, int lda, const u16* __restrict__ Bb, int ldb,
;                   int K, char* shm) {
;     ...
;     for (int ks = 0; ks < 2; ++ks) {
;       bf16x8 Bf[NF];
; #pragma unroll
;       for (int n = 0; n < NF; ++n) Bf[n] = *(const bf16x8*)(sB + b_off + n * 2048 + ks * 1024);
;       constexpr int MG = (NF == 2 && MF == 8) ? 4 : MF;
; #pragma unroll
;       for (int mg = 0; mg < MF / MG; ++mg) {
;         bf16x8 At[MG];
; #pragma unroll
;         for (int m = 0; m < MG; ++m) At[m] = *(const bf16x8*)(sA + a_off + (mg * MG + m) * 2048 + ks * 1024);
; #pragma unroll
;         for (int m = 0; m < MG; ++m)
; #pragma unroll
;           for (int n = 0; n < NF; ++n)
;             acc[mg * MG + m][n] = SWAP ? MFMA16(Bf[n], At[m], acc[mg * MG + m][n]) : MFMA16(At[m], Bf[n], acc[mg * MG + m][n]);
.Lppb_exit:
	v_mfma_f32_16x16x32_bf16 v[124:127], v[180:183], v[188:191], v[124:127]
	v_mfma_f32_16x16x32_bf16 v[120:123], v[184:187], v[188:191], v[120:123]
	v_mfma_f32_16x16x32_bf16 v[116:119], v[180:183], v[192:195], v[116:119]
	v_mfma_f32_16x16x32_bf16 v[112:115], v[184:187], v[192:195], v[112:115]
	v_mfma_f32_16x16x32_bf16 v[108:111], v[180:183], v[196:199], v[108:111]
	v_mfma_f32_16x16x32_bf16 v[104:107], v[184:187], v[196:199], v[104:107]
	v_mfma_f32_16x16x32_bf16 v[100:103], v[180:183], v[212:215], v[100:103]
	v_mfma_f32_16x16x32_bf16 v[96:99], v[184:187], v[212:215], v[96:99]
	v_mfma_f32_16x16x32_bf16 v[92:95], v[180:183], v[216:219], v[92:95]
	v_mfma_f32_16x16x32_bf16 v[88:91], v[184:187], v[216:219], v[88:91]
	v_mfma_f32_16x16x32_bf16 v[84:87], v[180:183], v[220:223], v[84:87]
	v_mfma_f32_16x16x32_bf16 v[80:83], v[184:187], v[220:223], v[80:83]
	v_mfma_f32_16x16x32_bf16 v[76:79], v[180:183], v[224:227], v[76:79]
	v_mfma_f32_16x16x32_bf16 v[72:75], v[184:187], v[224:227], v[72:75]
	v_mfma_f32_16x16x32_bf16 v[68:71], v[180:183], v[228:231], v[68:71]
	v_mfma_f32_16x16x32_bf16 v[64:67], v[184:187], v[228:231], v[64:67]
	s_nop 7
	s_nop 1
	s_branch .LBB0_934
